# speedup vs baseline: 1.0244x; 1.0244x over previous
.LBB0_44:
	s_cmpk_lt_i32 s19, 0x100
	s_cbranch_scc0 .LBB0_36
	s_mov_b32 s4, -1
	v_mbcnt_lo_u32_b32 v0, s4, 0
	v_mbcnt_hi_u32_b32 v0, s4, v0
	v_readlane_b32 s4, v255, 0
	s_nop 1
	v_or_b32_e32 v113, s4, v0
	s_ashr_i32 s4, s19, 31
	s_lshr_b32 s4, s4, 29
	s_add_i32 s33, s19, s4
	s_and_b32 s4, s33, -8
	s_sub_i32 s29, s19, s4
	s_cmp_gt_i32 s29, -1
	s_mov_b64 s[4:5], -1
	s_cbranch_scc0 .LBB0_47
	s_lshl_b32 s19, s29, 5
	s_mov_b64 s[4:5], 0

.LBB0_80:
	s_cmpk_lt_i32 s19, 0x400
	s_cbranch_scc0 .LBB0_72
	s_mov_b32 s4, -1
	v_mbcnt_lo_u32_b32 v0, s4, 0
	v_mbcnt_hi_u32_b32 v0, s4, v0
	v_readlane_b32 s4, v255, 0
	s_nop 1
	v_or_b32_e32 v113, s4, v0
	s_ashr_i32 s4, s19, 31
	s_lshr_b32 s4, s4, 29
	s_add_i32 s23, s19, s4
	s_and_b32 s4, s23, -8
	s_sub_i32 s22, s19, s4
	s_cmp_gt_i32 s22, -1
	s_mov_b64 s[4:5], -1
	s_cbranch_scc0 .LBB0_83
	s_lshl_b32 s19, s22, 7
	s_mov_b64 s[4:5], 0

.LBB0_92:
	v_mul_f32_e32 v214, 0x37000000, v176
	v_mul_f32_e32 v215, 0x37000000, v177
	v_lshlrev_b64 v[176:177], 2, v[4:5]
	v_lshl_add_u64 v[4:5], v[6:7], 0, v[176:177]
	v_mul_f32_e32 v194, 0x37000000, v154
	v_mul_f32_e32 v195, 0x37000000, v155
	v_mul_f32_e32 v196, 0x37000000, v156
	v_mul_f32_e32 v197, 0x37000000, v157
	global_load_dwordx4 v[154:157], v[4:5], off nt
	v_add_co_u32_e32 v6, vcc, s27, v4
	v_mul_f32_e32 v198, 0x37000000, v158
	s_nop 0
	v_addc_co_u32_e32 v7, vcc, 0, v5, vcc
	v_mul_f32_e32 v199, 0x37000000, v159
	v_mul_f32_e32 v200, 0x37000000, v160
	v_mul_f32_e32 v201, 0x37000000, v161
	global_load_dwordx4 v[158:161], v[6:7], off nt
	v_add_co_u32_e32 v6, vcc, s30, v4
	v_mul_f32_e32 v202, 0x37000000, v164
	s_nop 0
	v_addc_co_u32_e32 v7, vcc, 0, v5, vcc
	v_mul_f32_e32 v203, 0x37000000, v165
	v_mul_f32_e32 v204, 0x37000000, v166
	v_mul_f32_e32 v205, 0x37000000, v167
	global_load_dwordx4 v[164:167], v[6:7], off nt
	v_add_co_u32_e32 v6, vcc, s37, v4
	v_mul_f32_e32 v206, 0x37000000, v168
	s_nop 0
	v_addc_co_u32_e32 v7, vcc, 0, v5, vcc
	v_mul_f32_e32 v207, 0x37000000, v169
	v_mul_f32_e32 v208, 0x37000000, v170
	v_mul_f32_e32 v209, 0x37000000, v171
	global_load_dwordx4 v[168:171], v[6:7], off nt
	v_add_co_u32_e32 v6, vcc, s3, v4
	v_mul_f32_e32 v210, 0x37000000, v172
	s_nop 0
	v_addc_co_u32_e32 v7, vcc, 0, v5, vcc
	v_mul_f32_e32 v211, 0x37000000, v173
	v_mul_f32_e32 v212, 0x37000000, v174
	v_mul_f32_e32 v213, 0x37000000, v175
	global_load_dwordx4 v[172:175], v[6:7], off nt
	v_add_co_u32_e32 v6, vcc, s25, v4
	v_mul_f32_e32 v185, 0x37000000, v12
	s_nop 0
	v_addc_co_u32_e32 v7, vcc, 0, v5, vcc
	v_mul_f32_e32 v187, 0x37000000, v13
	v_mul_f32_e32 v192, 0x37000000, v14
	v_mul_f32_e32 v193, 0x37000000, v15
	global_load_dwordx4 v[12:15], v[6:7], off nt
	v_add_co_u32_e32 v6, vcc, s28, v4
	v_mul_f32_e32 v181, 0x37000000, v8
	s_nop 0
	v_addc_co_u32_e32 v7, vcc, 0, v5, vcc
	v_mul_f32_e32 v182, 0x37000000, v9
	v_mul_f32_e32 v183, 0x37000000, v10
	v_mul_f32_e32 v184, 0x37000000, v11
	global_load_dwordx4 v[8:11], v[6:7], off nt
	v_add_co_u32_e32 v4, vcc, s31, v4
	v_mul_f32_e32 v162, 0x37000000, v162
	s_nop 0
	v_addc_co_u32_e32 v5, vcc, 0, v5, vcc
	global_load_dwordx4 v[4:7], v[4:5], off nt
	s_barrier
	ds_write2_b32 v23, v181, v182 offset1:132
	ds_write2_b32 v113, v185, v187 offset0:16 offset1:148
	v_add_u32_e32 v181, 0x400, v23
	ds_write2_b32 v181, v183, v184 offset0:8 offset1:140
	v_add_u32_e32 v181, 0x400, v113
	ds_write2_b32 v181, v192, v193 offset0:24 offset1:156
	v_add_u32_e32 v181, 0x2000, v23
	ds_write2_b32 v181, v194, v195 offset0:64 offset1:196
	v_add_u32_e32 v181, 0x2000, v113
	ds_write2_b32 v181, v198, v199 offset0:80 offset1:212
	v_add_u32_e32 v181, 0x2400, v23
	ds_write2_b32 v181, v196, v197 offset0:72 offset1:204
	v_add_u32_e32 v181, 0x2400, v113
	ds_write2_b32 v181, v200, v201 offset0:88 offset1:220
	v_add_u32_e32 v181, 0x4200, v23
	ds_write2_b32 v181, v162, v202 offset1:132
	v_add_u32_e32 v162, 0x4200, v113
	ds_write2_b32 v162, v205, v206 offset0:16 offset1:148
	v_add_u32_e32 v162, 0x4600, v23
	ds_write2_b32 v162, v203, v204 offset0:8 offset1:140
	v_add_u32_e32 v162, 0x4600, v113
	ds_write2_b32 v162, v207, v208 offset0:24 offset1:156
	v_add_u32_e32 v162, 0x6200, v23
	ds_write2_b32 v162, v209, v210 offset0:64 offset1:196
	v_add_u32_e32 v162, 0x6200, v113
	ds_write2_b32 v162, v213, v214 offset0:80 offset1:212
	v_add_u32_e32 v162, 0x6600, v23
	v_mul_f32_e32 v178, 0x37000000, v178
	ds_write2_b32 v162, v211, v212 offset0:72 offset1:204
	v_add_u32_e32 v162, 0x6600, v113
	ds_write2_b32 v162, v215, v178 offset0:88 offset1:220
	v_add_u32_e32 v162, v180, v21
	v_lshlrev_b32_e32 v178, 2, v179
	v_mul_lo_u32 v162, v162, s39
	v_add3_u32 v162, 0, v178, v162
	s_waitcnt lgkmcnt(0)
	s_barrier
	v_lshl_add_u64 v[180:181], s[74:75], 0, v[176:177]
	ds_read_b128 v[176:179], v162
	v_lshl_add_u64 v[18:19], v[180:181], 0, v[18:19]
	v_lshlrev_b64 v[16:17], 13, v[16:17]
	v_lshl_add_u64 v[16:17], v[180:181], 0, v[16:17]
	s_add_i32 s33, s33, 1
	s_waitcnt vmcnt(0) lgkmcnt(0)
	v_pk_fma_f32 v[156:157], v[2:3], v[178:179], v[156:157]
	v_pk_fma_f32 v[154:155], v[0:1], v[176:177], v[154:155]
	global_store_dwordx4 v[18:19], v[154:157], off
	ds_read_b128 v[154:157], v162 offset:1056
	v_add_co_u32_e32 v18, vcc, s27, v16
	s_add_i32 s19, s19, 64
	s_nop 0
	v_addc_co_u32_e32 v19, vcc, 0, v17, vcc
	s_waitcnt lgkmcnt(0)
	v_pk_fma_f32 v[156:157], v[2:3], v[156:157], v[160:161]
	v_pk_fma_f32 v[154:155], v[0:1], v[154:155], v[158:159]
	global_store_dwordx4 v[18:19], v[154:157], off
	ds_read_b128 v[154:157], v162 offset:2112
	v_add_co_u32_e32 v18, vcc, s30, v16
	s_addk_i32 s23, 0x80
	s_nop 0
	v_addc_co_u32_e32 v19, vcc, 0, v17, vcc
	s_waitcnt lgkmcnt(0)
	v_pk_fma_f32 v[156:157], v[2:3], v[156:157], v[166:167]
	v_pk_fma_f32 v[154:155], v[0:1], v[154:155], v[164:165]
	global_store_dwordx4 v[18:19], v[154:157], off
	ds_read_b128 v[154:157], v162 offset:3168
	v_add_co_u32_e32 v18, vcc, s37, v16
	s_cmp_eq_u32 s33, 4
	s_nop 0
	v_addc_co_u32_e32 v19, vcc, 0, v17, vcc
	s_waitcnt lgkmcnt(0)
	v_pk_fma_f32 v[156:157], v[2:3], v[156:157], v[170:171]
	v_pk_fma_f32 v[154:155], v[0:1], v[154:155], v[168:169]
	global_store_dwordx4 v[18:19], v[154:157], off
	ds_read_b128 v[154:157], v162 offset:4224
	v_add_co_u32_e32 v18, vcc, s3, v16
	s_waitcnt lgkmcnt(0)
	v_pk_fma_f32 v[156:157], v[2:3], v[156:157], v[174:175]
	v_pk_fma_f32 v[154:155], v[0:1], v[154:155], v[172:173]
	v_addc_co_u32_e32 v19, vcc, 0, v17, vcc
	global_store_dwordx4 v[18:19], v[154:157], off
	ds_read_b128 v[154:157], v162 offset:5280
	v_add_co_u32_e32 v18, vcc, s25, v16
	s_waitcnt lgkmcnt(0)
	v_pk_fma_f32 v[14:15], v[2:3], v[156:157], v[14:15]
	v_pk_fma_f32 v[12:13], v[0:1], v[154:155], v[12:13]
	v_addc_co_u32_e32 v19, vcc, 0, v17, vcc
	global_store_dwordx4 v[18:19], v[12:15], off
	ds_read_b128 v[12:15], v162 offset:6336
	s_waitcnt lgkmcnt(0)
	v_pk_fma_f32 v[8:9], v[0:1], v[12:13], v[8:9]
	v_add_co_u32_e32 v12, vcc, s28, v16
	v_pk_fma_f32 v[10:11], v[2:3], v[14:15], v[10:11]
	s_nop 0
	v_addc_co_u32_e32 v13, vcc, 0, v17, vcc
	global_store_dwordx4 v[12:13], v[8:11], off
	ds_read_b128 v[8:11], v162 offset:7392
	s_waitcnt lgkmcnt(0)
	v_pk_fma_f32 v[0:1], v[0:1], v[8:9], v[4:5]
	v_add_co_u32_e32 v4, vcc, 0x1c000, v16
	v_pk_fma_f32 v[2:3], v[2:3], v[10:11], v[6:7]
	s_nop 0
	v_addc_co_u32_e32 v5, vcc, 0, v17, vcc
	global_store_dwordx4 v[4:5], v[0:3], off
	s_cbranch_scc1 .LBB0_71

.LBB0_122:
	s_mov_b64 s[4:5], -1
	s_and_b64 vcc, exec, s[84:85]
	s_barrier
	s_cbranch_vccz .LBB0_171
	s_mov_b32 s4, -1
	s_sub_i32 s20, 0, s11
	v_mbcnt_lo_u32_b32 v0, s4, 0
	v_mbcnt_hi_u32_b32 v0, s4, v0
	v_readlane_b32 s4, v255, 0
	v_mov_b32_e32 v114, v112
	v_mov_b32_e32 v115, v112
	v_or_b32_e32 v40, s4, v0
	s_movk_i32 s4, 0xffe0
	v_ashrrev_i32_e32 v41, 1, v40
	v_bfi_b32 v0, s4, v41, v40
	s_lshl_b64 s[4:5], s[20:21], 15
	v_ashrrev_i32_e32 v1, 31, v0
	s_add_u32 s6, s94, s4
	v_bfe_u32 v193, v40, 5, 1
	v_lshlrev_b64 v[0:1], 11, v[0:1]
	s_addc_u32 s7, s95, s5
	v_lshl_add_u64 v[0:1], s[98:99], 0, v[0:1]
	v_lshlrev_b32_e32 v162, 5, v193
	s_add_u32 s4, s96, s4
	v_lshl_add_u64 v[0:1], v[0:1], 0, v[162:163]
	v_lshlrev_b32_e32 v166, 4, v40
	s_addc_u32 s5, s97, s5
	global_load_dwordx4 v[126:129], v[0:1], off offset:16 nt
	global_load_dwordx4 v[122:125], v[0:1], off nt
	global_load_dwordx4 v[134:137], v[0:1], off offset:80 nt
	global_load_dwordx4 v[130:133], v[0:1], off offset:64 nt
	v_ashrrev_i32_e32 v2, 3, v40
	v_and_b32_e32 v0, 0x70, v166
	v_mov_b32_e32 v116, v112
	v_mov_b32_e32 v117, v112
	v_mov_b32_e32 v118, v112
	v_mov_b32_e32 v119, v112
	s_cmp_gt_i32 s11, 0
	v_lshl_or_b32 v168, v2, 9, v0
	v_mov_b32_e32 v113, v112
	v_mov_b64_e32 v[120:121], v[118:119]
	s_cselect_b32 s5, s93, s5
	s_cselect_b32 s4, s92, s4
	v_ashrrev_i32_e32 v167, 31, v166
	v_mov_b64_e32 v[118:119], v[116:117]
	v_mov_b64_e32 v[116:117], v[114:115]
	v_mov_b64_e32 v[114:115], v[112:113]
	s_cselect_b32 s7, s91, s7
	s_cselect_b32 s6, s90, s6
	v_lshl_add_u64 v[0:1], s[4:5], 0, v[166:167]
	v_ashrrev_i32_e32 v169, 31, v168
	global_load_dwordx4 v[146:149], v[0:1], off
	v_lshl_add_u64 v[0:1], s[6:7], 0, v[168:169]
	global_load_dwordx4 v[150:153], v[0:1], off
	v_and_b32_e32 v113, 31, v40
	v_lshlrev_b32_e32 v42, 1, v193
	v_and_b32_e32 v0, 7, v41
	v_lshlrev_b32_e32 v1, 7, v2
	v_lshrrev_b32_e32 v2, 1, v2
	v_xor_b32_e32 v2, v2, v40
	v_lshlrev_b32_e32 v165, 7, v113
	v_bitop3_b32 v4, v42, v41, 7 bitop3:0x78
	v_lshlrev_b32_e32 v2, 4, v2
	v_add_u32_e32 v5, 0, v165
	v_bitop3_b32 v6, v42, v0, 1 bitop3:0x36
	v_bitop3_b32 v7, v42, v0, 4 bitop3:0x36
	v_bitop3_b32 v0, v42, v0, 5 bitop3:0x36
	s_movk_i32 s4, 0x70
	v_lshlrev_b32_e32 v197, 4, v4
	v_add_u32_e32 v3, 0, v166
	v_and_or_b32 v1, v2, s4, v1
	v_lshlrev_b32_e32 v196, 4, v6
	v_lshlrev_b32_e32 v195, 4, v7
	v_lshlrev_b32_e32 v194, 4, v0
	v_add_u32_e32 v202, v5, v197
	v_add_u32_e32 v201, 0, v1
	v_add_u32_e32 v203, v5, v196
	v_add_u32_e32 v204, v5, v195
	v_add_u32_e32 v205, v5, v194
	s_waitcnt vmcnt(0)
	s_waitcnt vmcnt(1)
	ds_write_b128 v3, v[146:149]
	s_waitcnt vmcnt(0)
	ds_write_b128 v201, v[150:153] offset:32768
	s_waitcnt lgkmcnt(0)
	s_barrier
	ds_read_b128 v[0:3], v202 offset:32768
	ds_read_b128 v[32:35], v202 offset:36864
	ds_read_b128 v[4:7], v203 offset:32768
	ds_read_b128 v[36:39], v203 offset:36864
	ds_read_b128 v[44:47], v204 offset:32768
	ds_read_b128 v[52:55], v204 offset:36864
	ds_read_b128 v[48:51], v205 offset:32768
	ds_read_b128 v[56:59], v205 offset:36864
	s_waitcnt lgkmcnt(5)
	v_mfma_scale_f32_32x32x64_f8f6f4 v[16:31], v[0:7], v[122:129], 0, v186, v186 op_sel_hi:[0,0,0]
	s_waitcnt lgkmcnt(4)
	v_mfma_scale_f32_32x32x64_f8f6f4 v[0:15], v[32:39], v[122:129], 0, v186, v186 op_sel_hi:[0,0,0]
	s_waitcnt lgkmcnt(1)
	v_mfma_scale_f32_32x32x64_f8f6f4 v[16:31], v[44:51], v[130:137], v[16:31], v186, v186 op_sel_hi:[0,0,0]
	s_waitcnt lgkmcnt(0)
	v_mfma_scale_f32_32x32x64_f8f6f4 v[0:15], v[52:59], v[130:137], v[0:15], v186, v186 op_sel_hi:[0,0,0]
	s_nop 15
	s_nop 7
	v_max_f32_e32 v32, v17, v17
	v_max_f32_e32 v33, v16, v16
	v_max_f32_e32 v32, v33, v32
	v_max3_f32 v32, v32, v18, v19
	v_max3_f32 v32, v32, v20, v21
	v_max3_f32 v32, v32, v22, v23
	v_max3_f32 v32, v32, v24, v25
	v_max3_f32 v32, v32, v26, v27
	v_max3_f32 v32, v32, v28, v29
	v_max3_f32 v32, v32, v30, v31
	v_max3_f32 v32, v32, v0, v1
	v_max3_f32 v32, v32, v2, v3
	v_max3_f32 v32, v32, v4, v5
	v_max3_f32 v32, v32, v6, v7
	v_max3_f32 v32, v32, v8, v9
	v_max3_f32 v32, v32, v10, v11
	v_max3_f32 v32, v32, v12, v13
	v_max3_f32 v32, v32, v14, v15
	v_mov_b32_e32 v33, v32
	s_nop 1
	v_permlane32_swap_b32_e32 v32, v33
	v_max_f32_e32 v33, v33, v33
	v_max_f32_e32 v32, v32, v32
	v_max_f32_e32 v32, v32, v33
	v_add_f32_e32 v33, 0x7149f2ca, v32
	v_cmp_ge_f32_e32 vcc, s63, v33
	s_cmp_eq_u64 vcc, exec
	s_cbranch_scc0 .LBB0_234
	v_mov_b32_e32 v217, 1.0
	v_mov_b32_e32 v138, 0
	v_mov_b32_e32 v172, 0xf149f2ca
	s_cmp_lt_i32 s11, 2
	s_mov_b64 s[8:9], -1
	s_cbranch_scc0 .LBB0_126

.Lepi16_d:
	v_lshlrev_b64 v[84:85], 12, v[164:165]
	v_lshl_or_b32 v82, v193, 13, v113
	v_mov_b32_e32 v83, v163
	v_lshl_add_u64 v[86:87], s[86:87], 0, v[84:85]
	v_lshl_add_u64 v[84:85], s[88:89], 0, v[84:85]
	v_lshlrev_b32_e32 v80, 1, v82
	v_mov_b32_e32 v81, v163
	v_lshl_add_u64 v[84:85], v[84:85], 0, v[80:81]
	v_lshl_add_u64 v[86:87], v[86:87], 0, v[80:81]
	s_mov_b64 s[4:5], 0x1000
	v_lshl_add_u64 v[88:89], v[84:85], 0, s[4:5]
	global_load_ushort v94, v[88:89], off offset:-4096 nt
	global_load_ushort v95, v[88:89], off offset:-4032 nt
	global_load_ushort v96, v[88:89], off offset:-3968 nt
	global_load_ushort v97, v[88:89], off offset:-3904 nt
	global_load_ushort v98, v[88:89], off nt
	global_load_ushort v99, v[88:89], off offset:64 nt
	global_load_ushort v100, v[88:89], off offset:128 nt
	global_load_ushort v101, v[88:89], off offset:192 nt
	s_mov_b64 s[4:5], 0x3000
	v_lshl_add_u64 v[90:91], v[84:85], 0, s[4:5]
	global_load_ushort v102, v[90:91], off offset:-4096 nt
	global_load_ushort v103, v[90:91], off offset:-4032 nt
	global_load_ushort v104, v[90:91], off offset:-3968 nt
	global_load_ushort v105, v[90:91], off offset:-3904 nt
	global_load_ushort v106, v[90:91], off nt
	global_load_ushort v107, v[90:91], off offset:64 nt
	global_load_ushort v108, v[90:91], off offset:128 nt
	global_load_ushort v109, v[90:91], off offset:192 nt
	s_mov_b64 s[4:5], 0x9000
	v_lshl_add_u64 v[88:89], v[84:85], 0, s[4:5]
	global_load_ushort v110, v[88:89], off offset:-4096 nt
	global_load_ushort v111, v[88:89], off offset:-4032 nt
	global_load_ushort v114, v[88:89], off offset:-3968 nt
	global_load_ushort v115, v[88:89], off offset:-3904 nt
	global_load_ushort v116, v[88:89], off nt
	global_load_ushort v117, v[88:89], off offset:64 nt
	global_load_ushort v118, v[88:89], off offset:128 nt
	global_load_ushort v119, v[88:89], off offset:192 nt
	s_mov_b64 s[4:5], 0xb000
	v_lshl_add_u64 v[90:91], v[84:85], 0, s[4:5]
	global_load_ushort v120, v[90:91], off offset:-4096 nt
	global_load_ushort v121, v[90:91], off offset:-4032 nt
	global_load_ushort v122, v[90:91], off offset:-3968 nt
	global_load_ushort v123, v[90:91], off offset:-3904 nt
	global_load_ushort v124, v[90:91], off nt
	global_load_ushort v125, v[90:91], off offset:64 nt
	global_load_ushort v126, v[90:91], off offset:128 nt
	global_load_ushort v127, v[90:91], off offset:192 nt
	v_mul_f32_e32 v64, 0x41800000, v64
	v_mul_f32_e32 v65, 0x41800000, v65
	v_mul_f32_e32 v66, 0x41800000, v66
	v_mul_f32_e32 v67, 0x41800000, v67
	v_mul_f32_e32 v68, 0x41800000, v68
	v_mul_f32_e32 v69, 0x41800000, v69
	v_mul_f32_e32 v70, 0x41800000, v70
	v_mul_f32_e32 v71, 0x41800000, v71
	v_mul_f32_e32 v72, 0x41800000, v72
	v_mul_f32_e32 v73, 0x41800000, v73
	v_mul_f32_e32 v74, 0x41800000, v74
	v_mul_f32_e32 v75, 0x41800000, v75
	v_mul_f32_e32 v76, 0x41800000, v76
	v_mul_f32_e32 v77, 0x41800000, v77
	v_mul_f32_e32 v78, 0x41800000, v78
	v_mul_f32_e32 v79, 0x41800000, v79
	v_rcp_f32_e32 v64, v64
	v_rcp_f32_e32 v65, v65
	v_rcp_f32_e32 v66, v66
	v_rcp_f32_e32 v67, v67
	v_rcp_f32_e32 v68, v68
	v_rcp_f32_e32 v69, v69
	v_rcp_f32_e32 v70, v70
	v_rcp_f32_e32 v71, v71
	v_rcp_f32_e32 v72, v72
	v_rcp_f32_e32 v73, v73
	v_rcp_f32_e32 v74, v74
	v_rcp_f32_e32 v75, v75
	v_rcp_f32_e32 v76, v76
	v_rcp_f32_e32 v77, v77
	v_rcp_f32_e32 v78, v78
	v_rcp_f32_e32 v79, v79
	v_mul_f32_e32 v48, v48, v64
	v_mul_f32_e32 v32, v32, v64
	v_mul_f32_e32 v16, v16, v64
	v_mul_f32_e32 v0, v0, v64
	v_mul_f32_e32 v49, v49, v65
	v_mul_f32_e32 v33, v33, v65
	v_mul_f32_e32 v17, v17, v65
	v_mul_f32_e32 v1, v1, v65
	v_mul_f32_e32 v50, v50, v66
	v_mul_f32_e32 v34, v34, v66
	v_mul_f32_e32 v18, v18, v66
	v_mul_f32_e32 v2, v2, v66
	v_mul_f32_e32 v51, v51, v67
	v_mul_f32_e32 v35, v35, v67
	v_mul_f32_e32 v19, v19, v67
	v_mul_f32_e32 v3, v3, v67
	v_mul_f32_e32 v52, v52, v68
	v_mul_f32_e32 v36, v36, v68
	v_mul_f32_e32 v20, v20, v68
	v_mul_f32_e32 v4, v4, v68
	v_mul_f32_e32 v53, v53, v69
	v_mul_f32_e32 v37, v37, v69
	v_mul_f32_e32 v21, v21, v69
	v_mul_f32_e32 v5, v5, v69
	v_mul_f32_e32 v54, v54, v70
	v_mul_f32_e32 v38, v38, v70
	v_mul_f32_e32 v22, v22, v70
	v_mul_f32_e32 v6, v6, v70
	v_mul_f32_e32 v55, v55, v71
	v_mul_f32_e32 v39, v39, v71
	v_mul_f32_e32 v23, v23, v71
	v_mul_f32_e32 v7, v7, v71
	v_mul_f32_e32 v56, v56, v72
	v_mul_f32_e32 v40, v40, v72
	v_mul_f32_e32 v24, v24, v72
	v_mul_f32_e32 v8, v8, v72
	v_mul_f32_e32 v57, v57, v73
	v_mul_f32_e32 v41, v41, v73
	v_mul_f32_e32 v25, v25, v73
	v_mul_f32_e32 v9, v9, v73
	v_mul_f32_e32 v58, v58, v74
	v_mul_f32_e32 v42, v42, v74
	v_mul_f32_e32 v26, v26, v74
	v_mul_f32_e32 v10, v10, v74
	v_mul_f32_e32 v59, v59, v75
	v_mul_f32_e32 v43, v43, v75
	v_mul_f32_e32 v27, v27, v75
	v_mul_f32_e32 v11, v11, v75
	v_mul_f32_e32 v60, v60, v76
	v_mul_f32_e32 v44, v44, v76
	v_mul_f32_e32 v28, v28, v76
	v_mul_f32_e32 v12, v12, v76
	v_mul_f32_e32 v61, v61, v77
	v_mul_f32_e32 v45, v45, v77
	v_mul_f32_e32 v29, v29, v77
	v_mul_f32_e32 v13, v13, v77
	v_mul_f32_e32 v62, v62, v78
	v_mul_f32_e32 v46, v46, v78
	v_mul_f32_e32 v30, v30, v78
	v_mul_f32_e32 v14, v14, v78
	v_mul_f32_e32 v63, v63, v79
	v_mul_f32_e32 v47, v47, v79
	v_mul_f32_e32 v31, v31, v79
	v_mul_f32_e32 v15, v15, v79
	s_waitcnt vmcnt(16)
	s_mov_b64 s[4:5], 0x1000
	v_lshl_add_u64 v[80:81], v[86:87], 0, s[4:5]
	s_mov_b64 s[4:5], 0x3000
	v_lshl_add_u64 v[92:93], v[86:87], 0, s[4:5]
	v_lshlrev_b32_e32 v94, 16, v94
	v_mul_f32_e32 v94, v48, v94
	v_cvt_pk_bf16_f32 v94, v94, v94
	global_store_short v[80:81], v94, off offset:-4096
	v_lshlrev_b32_e32 v95, 16, v95
	v_mul_f32_e32 v95, v32, v95
	v_cvt_pk_bf16_f32 v95, v95, v95
	global_store_short v[80:81], v95, off offset:-4032
	v_lshlrev_b32_e32 v96, 16, v96
	v_mul_f32_e32 v96, v16, v96
	v_cvt_pk_bf16_f32 v96, v96, v96
	global_store_short v[80:81], v96, off offset:-3968
	v_lshlrev_b32_e32 v97, 16, v97
	v_mul_f32_e32 v97, v0, v97
	v_cvt_pk_bf16_f32 v97, v97, v97
	global_store_short v[80:81], v97, off offset:-3904
	v_lshlrev_b32_e32 v98, 16, v98
	v_mul_f32_e32 v98, v49, v98
	v_cvt_pk_bf16_f32 v98, v98, v98
	global_store_short v[80:81], v98, off
	v_lshlrev_b32_e32 v99, 16, v99
	v_mul_f32_e32 v99, v33, v99
	v_cvt_pk_bf16_f32 v99, v99, v99
	global_store_short v[80:81], v99, off offset:64
	v_lshlrev_b32_e32 v100, 16, v100
	v_mul_f32_e32 v100, v17, v100
	v_cvt_pk_bf16_f32 v100, v100, v100
	global_store_short v[80:81], v100, off offset:128
	v_lshlrev_b32_e32 v101, 16, v101
	v_mul_f32_e32 v101, v1, v101
	v_cvt_pk_bf16_f32 v101, v101, v101
	global_store_short v[80:81], v101, off offset:192
	v_lshlrev_b32_e32 v102, 16, v102
	v_mul_f32_e32 v102, v50, v102
	v_cvt_pk_bf16_f32 v102, v102, v102
	global_store_short v[92:93], v102, off offset:-4096
	v_lshlrev_b32_e32 v103, 16, v103
	v_mul_f32_e32 v103, v34, v103
	v_cvt_pk_bf16_f32 v103, v103, v103
	global_store_short v[92:93], v103, off offset:-4032
	v_lshlrev_b32_e32 v104, 16, v104
	v_mul_f32_e32 v104, v18, v104
	v_cvt_pk_bf16_f32 v104, v104, v104
	global_store_short v[92:93], v104, off offset:-3968
	v_lshlrev_b32_e32 v105, 16, v105
	v_mul_f32_e32 v105, v2, v105
	v_cvt_pk_bf16_f32 v105, v105, v105
	global_store_short v[92:93], v105, off offset:-3904
	v_lshlrev_b32_e32 v106, 16, v106
	v_mul_f32_e32 v106, v51, v106
	v_cvt_pk_bf16_f32 v106, v106, v106
	global_store_short v[92:93], v106, off
	v_lshlrev_b32_e32 v107, 16, v107
	v_mul_f32_e32 v107, v35, v107
	v_cvt_pk_bf16_f32 v107, v107, v107
	global_store_short v[92:93], v107, off offset:64
	v_lshlrev_b32_e32 v108, 16, v108
	v_mul_f32_e32 v108, v19, v108
	v_cvt_pk_bf16_f32 v108, v108, v108
	global_store_short v[92:93], v108, off offset:128
	v_lshlrev_b32_e32 v109, 16, v109
	v_mul_f32_e32 v109, v3, v109
	v_cvt_pk_bf16_f32 v109, v109, v109
	global_store_short v[92:93], v109, off offset:192
	s_mov_b64 s[4:5], 0x11000
	v_lshl_add_u64 v[88:89], v[84:85], 0, s[4:5]
	global_load_ushort v128, v[88:89], off offset:-4096 nt
	global_load_ushort v129, v[88:89], off offset:-4032 nt
	global_load_ushort v130, v[88:89], off offset:-3968 nt
	global_load_ushort v131, v[88:89], off offset:-3904 nt
	global_load_ushort v132, v[88:89], off nt
	global_load_ushort v133, v[88:89], off offset:64 nt
	global_load_ushort v134, v[88:89], off offset:128 nt
	global_load_ushort v135, v[88:89], off offset:192 nt
	s_mov_b64 s[4:5], 0x13000
	v_lshl_add_u64 v[90:91], v[84:85], 0, s[4:5]
	global_load_ushort v136, v[90:91], off offset:-4096 nt
	global_load_ushort v137, v[90:91], off offset:-4032 nt
	global_load_ushort v138, v[90:91], off offset:-3968 nt
	global_load_ushort v139, v[90:91], off offset:-3904 nt
	global_load_ushort v140, v[90:91], off nt
	global_load_ushort v141, v[90:91], off offset:64 nt
	global_load_ushort v142, v[90:91], off offset:128 nt
	global_load_ushort v143, v[90:91], off offset:192 nt
	s_waitcnt vmcnt(32)
	s_mov_b64 s[4:5], 0x9000
	v_lshl_add_u64 v[80:81], v[86:87], 0, s[4:5]
	s_mov_b64 s[4:5], 0xb000
	v_lshl_add_u64 v[92:93], v[86:87], 0, s[4:5]
	v_lshlrev_b32_e32 v110, 16, v110
	v_mul_f32_e32 v110, v52, v110
	v_cvt_pk_bf16_f32 v110, v110, v110
	global_store_short v[80:81], v110, off offset:-4096
	v_lshlrev_b32_e32 v111, 16, v111
	v_mul_f32_e32 v111, v36, v111
	v_cvt_pk_bf16_f32 v111, v111, v111
	global_store_short v[80:81], v111, off offset:-4032
	v_lshlrev_b32_e32 v114, 16, v114
	v_mul_f32_e32 v114, v20, v114
	v_cvt_pk_bf16_f32 v114, v114, v114
	global_store_short v[80:81], v114, off offset:-3968
	v_lshlrev_b32_e32 v115, 16, v115
	v_mul_f32_e32 v115, v4, v115
	v_cvt_pk_bf16_f32 v115, v115, v115
	global_store_short v[80:81], v115, off offset:-3904
	v_lshlrev_b32_e32 v116, 16, v116
	v_mul_f32_e32 v116, v53, v116
	v_cvt_pk_bf16_f32 v116, v116, v116
	global_store_short v[80:81], v116, off
	v_lshlrev_b32_e32 v117, 16, v117
	v_mul_f32_e32 v117, v37, v117
	v_cvt_pk_bf16_f32 v117, v117, v117
	global_store_short v[80:81], v117, off offset:64
	v_lshlrev_b32_e32 v118, 16, v118
	v_mul_f32_e32 v118, v21, v118
	v_cvt_pk_bf16_f32 v118, v118, v118
	global_store_short v[80:81], v118, off offset:128
	v_lshlrev_b32_e32 v119, 16, v119
	v_mul_f32_e32 v119, v5, v119
	v_cvt_pk_bf16_f32 v119, v119, v119
	global_store_short v[80:81], v119, off offset:192
	v_lshlrev_b32_e32 v120, 16, v120
	v_mul_f32_e32 v120, v54, v120
	v_cvt_pk_bf16_f32 v120, v120, v120
	global_store_short v[92:93], v120, off offset:-4096
	v_lshlrev_b32_e32 v121, 16, v121
	v_mul_f32_e32 v121, v38, v121
	v_cvt_pk_bf16_f32 v121, v121, v121
	global_store_short v[92:93], v121, off offset:-4032
	v_lshlrev_b32_e32 v122, 16, v122
	v_mul_f32_e32 v122, v22, v122
	v_cvt_pk_bf16_f32 v122, v122, v122
	global_store_short v[92:93], v122, off offset:-3968
	v_lshlrev_b32_e32 v123, 16, v123
	v_mul_f32_e32 v123, v6, v123
	v_cvt_pk_bf16_f32 v123, v123, v123
	global_store_short v[92:93], v123, off offset:-3904
	v_lshlrev_b32_e32 v124, 16, v124
	v_mul_f32_e32 v124, v55, v124
	v_cvt_pk_bf16_f32 v124, v124, v124
	global_store_short v[92:93], v124, off
	v_lshlrev_b32_e32 v125, 16, v125
	v_mul_f32_e32 v125, v39, v125
	v_cvt_pk_bf16_f32 v125, v125, v125
	global_store_short v[92:93], v125, off offset:64
	v_lshlrev_b32_e32 v126, 16, v126
	v_mul_f32_e32 v126, v23, v126
	v_cvt_pk_bf16_f32 v126, v126, v126
	global_store_short v[92:93], v126, off offset:128
	v_lshlrev_b32_e32 v127, 16, v127
	v_mul_f32_e32 v127, v7, v127
	v_cvt_pk_bf16_f32 v127, v127, v127
	global_store_short v[92:93], v127, off offset:192
	s_waitcnt vmcnt(32)
	s_mov_b64 s[4:5], 0x19000
	v_lshl_add_u64 v[88:89], v[84:85], 0, s[4:5]
	global_load_ushort v144, v[88:89], off offset:-4096 nt
	global_load_ushort v145, v[88:89], off offset:-4032 nt
	global_load_ushort v146, v[88:89], off offset:-3968 nt
	global_load_ushort v147, v[88:89], off offset:-3904 nt
	global_load_ushort v148, v[88:89], off nt
	global_load_ushort v149, v[88:89], off offset:64 nt
	global_load_ushort v150, v[88:89], off offset:128 nt
	global_load_ushort v151, v[88:89], off offset:192 nt
	s_mov_b64 s[4:5], 0x1b000
	v_lshl_add_u64 v[90:91], v[84:85], 0, s[4:5]
	global_load_ushort v152, v[90:91], off offset:-4096 nt
	global_load_ushort v153, v[90:91], off offset:-4032 nt
	global_load_ushort v154, v[90:91], off offset:-3968 nt
	global_load_ushort v155, v[90:91], off offset:-3904 nt
	global_load_ushort v156, v[90:91], off nt
	global_load_ushort v157, v[90:91], off offset:64 nt
	global_load_ushort v158, v[90:91], off offset:128 nt
	global_load_ushort v159, v[90:91], off offset:192 nt
	s_waitcnt vmcnt(32)
	s_mov_b64 s[4:5], 0x11000
	v_lshl_add_u64 v[80:81], v[86:87], 0, s[4:5]
	s_mov_b64 s[4:5], 0x13000
	v_lshl_add_u64 v[92:93], v[86:87], 0, s[4:5]
	v_lshlrev_b32_e32 v128, 16, v128
	v_mul_f32_e32 v128, v56, v128
	v_cvt_pk_bf16_f32 v128, v128, v128
	global_store_short v[80:81], v128, off offset:-4096
	v_lshlrev_b32_e32 v129, 16, v129
	v_mul_f32_e32 v129, v40, v129
	v_cvt_pk_bf16_f32 v129, v129, v129
	global_store_short v[80:81], v129, off offset:-4032
	v_lshlrev_b32_e32 v130, 16, v130
	v_mul_f32_e32 v130, v24, v130
	v_cvt_pk_bf16_f32 v130, v130, v130
	global_store_short v[80:81], v130, off offset:-3968
	v_lshlrev_b32_e32 v131, 16, v131
	v_mul_f32_e32 v131, v8, v131
	v_cvt_pk_bf16_f32 v131, v131, v131
	global_store_short v[80:81], v131, off offset:-3904
	v_lshlrev_b32_e32 v132, 16, v132
	v_mul_f32_e32 v132, v57, v132
	v_cvt_pk_bf16_f32 v132, v132, v132
	global_store_short v[80:81], v132, off
	v_lshlrev_b32_e32 v133, 16, v133
	v_mul_f32_e32 v133, v41, v133
	v_cvt_pk_bf16_f32 v133, v133, v133
	global_store_short v[80:81], v133, off offset:64
	v_lshlrev_b32_e32 v134, 16, v134
	v_mul_f32_e32 v134, v25, v134
	v_cvt_pk_bf16_f32 v134, v134, v134
	global_store_short v[80:81], v134, off offset:128
	v_lshlrev_b32_e32 v135, 16, v135
	v_mul_f32_e32 v135, v9, v135
	v_cvt_pk_bf16_f32 v135, v135, v135
	global_store_short v[80:81], v135, off offset:192
	v_lshlrev_b32_e32 v136, 16, v136
	v_mul_f32_e32 v136, v58, v136
	v_cvt_pk_bf16_f32 v136, v136, v136
	global_store_short v[92:93], v136, off offset:-4096
	v_lshlrev_b32_e32 v137, 16, v137
	v_mul_f32_e32 v137, v42, v137
	v_cvt_pk_bf16_f32 v137, v137, v137
	global_store_short v[92:93], v137, off offset:-4032
	v_lshlrev_b32_e32 v138, 16, v138
	v_mul_f32_e32 v138, v26, v138
	v_cvt_pk_bf16_f32 v138, v138, v138
	global_store_short v[92:93], v138, off offset:-3968
	v_lshlrev_b32_e32 v139, 16, v139
	v_mul_f32_e32 v139, v10, v139
	v_cvt_pk_bf16_f32 v139, v139, v139
	global_store_short v[92:93], v139, off offset:-3904
	v_lshlrev_b32_e32 v140, 16, v140
	v_mul_f32_e32 v140, v59, v140
	v_cvt_pk_bf16_f32 v140, v140, v140
	global_store_short v[92:93], v140, off
	v_lshlrev_b32_e32 v141, 16, v141
	v_mul_f32_e32 v141, v43, v141
	v_cvt_pk_bf16_f32 v141, v141, v141
	global_store_short v[92:93], v141, off offset:64
	v_lshlrev_b32_e32 v142, 16, v142
	v_mul_f32_e32 v142, v27, v142
	v_cvt_pk_bf16_f32 v142, v142, v142
	global_store_short v[92:93], v142, off offset:128
	v_lshlrev_b32_e32 v143, 16, v143
	v_mul_f32_e32 v143, v11, v143
	v_cvt_pk_bf16_f32 v143, v143, v143
	global_store_short v[92:93], v143, off offset:192
	s_waitcnt vmcnt(16)
	s_mov_b64 s[4:5], 0x19000
	v_lshl_add_u64 v[80:81], v[86:87], 0, s[4:5]
	s_mov_b64 s[4:5], 0x1b000
	v_lshl_add_u64 v[92:93], v[86:87], 0, s[4:5]
	v_lshlrev_b32_e32 v144, 16, v144
	v_mul_f32_e32 v144, v60, v144
	v_cvt_pk_bf16_f32 v144, v144, v144
	global_store_short v[80:81], v144, off offset:-4096
	v_lshlrev_b32_e32 v145, 16, v145
	v_mul_f32_e32 v145, v44, v145
	v_cvt_pk_bf16_f32 v145, v145, v145
	global_store_short v[80:81], v145, off offset:-4032
	v_lshlrev_b32_e32 v146, 16, v146
	v_mul_f32_e32 v146, v28, v146
	v_cvt_pk_bf16_f32 v146, v146, v146
	global_store_short v[80:81], v146, off offset:-3968
	v_lshlrev_b32_e32 v147, 16, v147
	v_mul_f32_e32 v147, v12, v147
	v_cvt_pk_bf16_f32 v147, v147, v147
	global_store_short v[80:81], v147, off offset:-3904
	v_lshlrev_b32_e32 v148, 16, v148
	v_mul_f32_e32 v148, v61, v148
	v_cvt_pk_bf16_f32 v148, v148, v148
	global_store_short v[80:81], v148, off
	v_lshlrev_b32_e32 v149, 16, v149
	v_mul_f32_e32 v149, v45, v149
	v_cvt_pk_bf16_f32 v149, v149, v149
	global_store_short v[80:81], v149, off offset:64
	v_lshlrev_b32_e32 v150, 16, v150
	v_mul_f32_e32 v150, v29, v150
	v_cvt_pk_bf16_f32 v150, v150, v150
	global_store_short v[80:81], v150, off offset:128
	v_lshlrev_b32_e32 v151, 16, v151
	v_mul_f32_e32 v151, v13, v151
	v_cvt_pk_bf16_f32 v151, v151, v151
	global_store_short v[80:81], v151, off offset:192
	v_lshlrev_b32_e32 v152, 16, v152
	v_mul_f32_e32 v152, v62, v152
	v_cvt_pk_bf16_f32 v152, v152, v152
	global_store_short v[92:93], v152, off offset:-4096
	v_lshlrev_b32_e32 v153, 16, v153
	v_mul_f32_e32 v153, v46, v153
	v_cvt_pk_bf16_f32 v153, v153, v153
	global_store_short v[92:93], v153, off offset:-4032
	v_lshlrev_b32_e32 v154, 16, v154
	v_mul_f32_e32 v154, v30, v154
	v_cvt_pk_bf16_f32 v154, v154, v154
	global_store_short v[92:93], v154, off offset:-3968
	v_lshlrev_b32_e32 v155, 16, v155
	v_mul_f32_e32 v155, v14, v155
	v_cvt_pk_bf16_f32 v155, v155, v155
	global_store_short v[92:93], v155, off offset:-3904
	v_lshlrev_b32_e32 v156, 16, v156
	v_mul_f32_e32 v156, v63, v156
	v_cvt_pk_bf16_f32 v156, v156, v156
	global_store_short v[92:93], v156, off
	v_lshlrev_b32_e32 v157, 16, v157
	v_mul_f32_e32 v157, v47, v157
	v_cvt_pk_bf16_f32 v157, v157, v157
	global_store_short v[92:93], v157, off offset:64
	v_lshlrev_b32_e32 v158, 16, v158
	v_mul_f32_e32 v158, v31, v158
	v_cvt_pk_bf16_f32 v158, v158, v158
	global_store_short v[92:93], v158, off offset:128
	v_lshlrev_b32_e32 v159, 16, v159
	v_mul_f32_e32 v159, v15, v159
	v_cvt_pk_bf16_f32 v159, v159, v159
	global_store_short v[92:93], v159, off offset:192
	s_branch .LBB0_170

.LBB0_171:
	s_and_b64 vcc, exec, s[4:5]
	s_cbranch_vccz .LBB0_115
	s_mov_b32 s6, -1
	s_cmp_lg_u32 s35, 0
	v_mbcnt_lo_u32_b32 v0, s6, 0
	v_mbcnt_hi_u32_b32 v0, s6, v0
	v_readlane_b32 s6, v255, 0
	s_cselect_b64 s[22:23], -1, 0
	s_cmp_eq_u32 s35, 0
	v_or_b32_e32 v40, s6, v0
	s_cselect_b64 s[4:5], -1, 0
	v_ashrrev_i32_e32 v4, 6, v40
	v_and_b32_e32 v193, 31, v40
	v_readfirstlane_b32 s6, v4
	s_lshl_b32 s13, s6, 5
	s_sub_i32 s18, 0, s13
	s_cmp_gt_i32 s11, 0
	v_lshlrev_b32_e32 v164, 5, v4
	s_cselect_b64 s[6:7], -1, 0
	s_sub_i32 s20, 0, s11
	v_or_b32_e32 v0, v164, v193
	s_lshl_b64 s[8:9], s[20:21], 15
	v_ashrrev_i32_e32 v1, 31, v0
	s_add_u32 s12, s94, s8
	v_bfe_u32 v194, v40, 5, 1
	v_lshlrev_b64 v[2:3], 11, v[0:1]
	s_addc_u32 s19, s95, s9
	v_lshl_add_u64 v[2:3], s[98:99], 0, v[2:3]
	v_lshlrev_b32_e32 v162, 5, v194
	s_add_u32 s20, s96, s8
	v_lshl_add_u64 v[2:3], v[2:3], 0, v[162:163]
	v_lshlrev_b32_e32 v168, 4, v40
	s_addc_u32 s29, s97, s9
	global_load_dwordx4 v[126:129], v[2:3], off offset:16 nt
	global_load_dwordx4 v[122:125], v[2:3], off nt
	global_load_dwordx4 v[134:137], v[2:3], off offset:80 nt
	global_load_dwordx4 v[130:133], v[2:3], off offset:64 nt
	v_ashrrev_i32_e32 v1, 3, v40
	v_and_b32_e32 v2, 0x70, v168
	v_mov_b32_e32 v114, v112
	v_mov_b32_e32 v115, v112
	v_mov_b32_e32 v116, v112
	v_mov_b32_e32 v117, v112
	v_mov_b32_e32 v118, v112
	v_mov_b32_e32 v119, v112
	s_and_b64 s[8:9], s[6:7], exec
	v_lshl_or_b32 v170, v1, 9, v2
	v_mov_b32_e32 v113, v112
	v_mov_b64_e32 v[120:121], v[118:119]
	s_cselect_b32 s9, s93, s29
	s_cselect_b32 s8, s92, s20
	v_ashrrev_i32_e32 v169, 31, v168
	v_mov_b64_e32 v[118:119], v[116:117]
	v_mov_b64_e32 v[116:117], v[114:115]
	v_mov_b64_e32 v[114:115], v[112:113]
	s_cselect_b32 s35, s91, s19
	s_cselect_b32 s34, s90, s12
	v_lshl_add_u64 v[2:3], s[8:9], 0, v[168:169]
	v_ashrrev_i32_e32 v171, 31, v170
	global_load_dwordx4 v[146:149], v[2:3], off
	v_lshl_add_u64 v[2:3], s[34:35], 0, v[170:171]
	global_load_dwordx4 v[150:153], v[2:3], off
	v_lshlrev_b32_e32 v41, 1, v194
	s_waitcnt vmcnt(6)
	v_readfirstlane_b32 s35, v192
	v_lshrrev_b32_e32 v7, 1, v40
	v_and_b32_e32 v2, 7, v7
	v_lshlrev_b32_e32 v3, 7, v1
	v_lshrrev_b32_e32 v1, 1, v1
	v_xor_b32_e32 v1, v1, v40
	v_lshlrev_b32_e32 v192, 7, v193
	v_bitop3_b32 v5, v41, v7, 7 bitop3:0x78
	v_lshlrev_b32_e32 v1, 4, v1
	v_add_u32_e32 v6, 0, v192
	v_bitop3_b32 v7, v41, v2, 1 bitop3:0x36
	v_bitop3_b32 v8, v41, v2, 4 bitop3:0x36
	v_bitop3_b32 v2, v41, v2, 5 bitop3:0x36
	s_movk_i32 s8, 0x70
	v_lshlrev_b32_e32 v198, 4, v5
	v_add_u32_e32 v4, 0, v168
	v_and_or_b32 v1, v1, s8, v3
	v_lshlrev_b32_e32 v197, 4, v7
	v_lshlrev_b32_e32 v196, 4, v8
	v_lshlrev_b32_e32 v195, 4, v2
	v_add_u32_e32 v203, v6, v198
	v_sub_u32_e32 v165, s52, v0
	v_add_u32_e32 v202, 0, v1
	v_add_u32_e32 v204, v6, v197
	v_add_u32_e32 v205, v6, v196
	v_add_u32_e32 v206, v6, v195
	s_waitcnt vmcnt(0)
	s_or_b64 s[4:5], s[6:7], s[4:5]
	s_and_b64 vcc, exec, s[4:5]
	s_waitcnt vmcnt(1)
	ds_write_b128 v4, v[146:149]
	s_waitcnt vmcnt(0)
	ds_write_b128 v202, v[150:153] offset:32768
	s_waitcnt lgkmcnt(0)
	s_barrier
	ds_read_b128 v[0:3], v203 offset:32768
	ds_read_b128 v[32:35], v203 offset:36864
	ds_read_b128 v[4:7], v204 offset:32768
	ds_read_b128 v[36:39], v204 offset:36864
	ds_read_b128 v[42:45], v205 offset:32768
	ds_read_b128 v[50:53], v205 offset:36864
	ds_read_b128 v[46:49], v206 offset:32768
	ds_read_b128 v[54:57], v206 offset:36864
	s_waitcnt lgkmcnt(5)
	v_mfma_scale_f32_32x32x64_f8f6f4 v[16:31], v[0:7], v[122:129], 0, v186, v186 op_sel_hi:[0,0,0]
	s_waitcnt lgkmcnt(4)
	v_mfma_scale_f32_32x32x64_f8f6f4 v[0:15], v[32:39], v[122:129], 0, v186, v186 op_sel_hi:[0,0,0]
	s_waitcnt lgkmcnt(1)
	v_mfma_scale_f32_32x32x64_f8f6f4 v[16:31], v[42:49], v[130:137], v[16:31], v186, v186 op_sel_hi:[0,0,0]
	s_waitcnt lgkmcnt(0)
	v_mfma_scale_f32_32x32x64_f8f6f4 v[0:15], v[50:57], v[130:137], v[0:15], v186, v186 op_sel_hi:[0,0,0]
	s_nop 15
	s_nop 7
	s_cbranch_vccnz .LBB0_175
	s_lshl_b32 s4, s11, 6
	s_sub_i32 s5, s52, s4
	s_add_i32 s5, s5, s18
	s_addk_i32 s5, 0xffbe
	s_cmp_gt_u32 s5, 0xffffff5c
	s_cbranch_scc1 .LBB0_175
	s_sub_i32 s4, 0, s4
	v_lshl_or_b32 v32, v194, 2, s4
	v_add_u32_e32 v32, v32, v165
	v_add_u32_e32 v33, 0xffffff7f, v32
	v_cmp_lt_u32_e32 vcc, s67, v33
	v_add_u32_e32 v33, 0xffffff9f, v32
	s_nop 0
	v_cndmask_b32_e32 v16, v191, v16, vcc
	v_cmp_lt_u32_e32 vcc, s67, v33
	v_add_u32_e32 v33, 0xffffff80, v32
	s_nop 0
	v_cndmask_b32_e32 v0, v191, v0, vcc
	v_cmp_lt_u32_e32 vcc, s67, v33
	v_add_u32_e32 v33, 0xffffffa0, v32
	s_nop 0
	v_cndmask_b32_e32 v17, v191, v17, vcc
	v_cmp_lt_u32_e32 vcc, s67, v33
	v_add_u32_e32 v33, 0xffffff81, v32
	s_nop 0
	v_cndmask_b32_e32 v1, v191, v1, vcc
	v_cmp_lt_u32_e32 vcc, s67, v33
	v_add_u32_e32 v33, 0xffffffa1, v32
	s_nop 0
	v_cndmask_b32_e32 v18, v191, v18, vcc
	v_cmp_lt_u32_e32 vcc, s67, v33
	v_add_u32_e32 v33, 0xffffff82, v32
	s_nop 0
	v_cndmask_b32_e32 v2, v191, v2, vcc
	v_cmp_lt_u32_e32 vcc, s67, v33
	v_add_u32_e32 v33, 0xffffffa2, v32
	s_nop 0
	v_cndmask_b32_e32 v19, v191, v19, vcc
	v_cmp_lt_u32_e32 vcc, s67, v33
	v_add_u32_e32 v33, 0xffffff87, v32
	s_nop 0
	v_cndmask_b32_e32 v3, v191, v3, vcc
	v_cmp_lt_u32_e32 vcc, s67, v33
	v_add_u32_e32 v33, 0xffffffa7, v32
	s_nop 0
	v_cndmask_b32_e32 v20, v191, v20, vcc
	v_cmp_lt_u32_e32 vcc, s67, v33
	v_add_u32_e32 v33, 0xffffff88, v32
	s_nop 0
	v_cndmask_b32_e32 v4, v191, v4, vcc
	v_cmp_lt_u32_e32 vcc, s67, v33
	v_add_u32_e32 v33, 0xffffffa8, v32
	s_nop 0
	v_cndmask_b32_e32 v21, v191, v21, vcc
	v_cmp_lt_u32_e32 vcc, s67, v33
	v_add_u32_e32 v33, 0xffffff89, v32
	s_nop 0
	v_cndmask_b32_e32 v5, v191, v5, vcc
	v_cmp_lt_u32_e32 vcc, s67, v33
	v_add_u32_e32 v33, 0xffffffa9, v32
	s_nop 0
	v_cndmask_b32_e32 v22, v191, v22, vcc
	v_cmp_lt_u32_e32 vcc, s67, v33
	v_add_u32_e32 v33, 0xffffff8a, v32
	s_nop 0
	v_cndmask_b32_e32 v6, v191, v6, vcc
	v_cmp_lt_u32_e32 vcc, s67, v33
	v_add_u32_e32 v33, 0xffffffaa, v32
	s_nop 0
	v_cndmask_b32_e32 v23, v191, v23, vcc
	v_cmp_lt_u32_e32 vcc, s67, v33
	v_add_u32_e32 v33, 0xffffff8f, v32
	s_nop 0
	v_cndmask_b32_e32 v7, v191, v7, vcc
	v_cmp_lt_u32_e32 vcc, s67, v33
	v_add_u32_e32 v33, 0xffffffaf, v32
	s_nop 0
	v_cndmask_b32_e32 v24, v191, v24, vcc
	v_cmp_lt_u32_e32 vcc, s67, v33
	v_add_u32_e32 v33, 0xffffff90, v32
	s_nop 0
	v_cndmask_b32_e32 v8, v191, v8, vcc
	v_cmp_lt_u32_e32 vcc, s67, v33
	v_add_u32_e32 v33, 0xffffffb0, v32
	s_nop 0
	v_cndmask_b32_e32 v25, v191, v25, vcc
	v_cmp_lt_u32_e32 vcc, s67, v33
	v_add_u32_e32 v33, 0xffffff91, v32
	s_nop 0
	v_cndmask_b32_e32 v9, v191, v9, vcc
	v_cmp_lt_u32_e32 vcc, s67, v33
	v_add_u32_e32 v33, 0xffffffb1, v32
	s_nop 0
	v_cndmask_b32_e32 v26, v191, v26, vcc
	v_cmp_lt_u32_e32 vcc, s67, v33
	v_add_u32_e32 v33, 0xffffff92, v32
	s_nop 0
	v_cndmask_b32_e32 v10, v191, v10, vcc
	v_cmp_lt_u32_e32 vcc, s67, v33
	v_add_u32_e32 v33, 0xffffffb2, v32
	s_nop 0
	v_cndmask_b32_e32 v27, v191, v27, vcc
	v_cmp_lt_u32_e32 vcc, s67, v33
	v_add_u32_e32 v33, 0xffffff97, v32
	s_nop 0
	v_cndmask_b32_e32 v11, v191, v11, vcc
	v_cmp_lt_u32_e32 vcc, s67, v33
	v_add_u32_e32 v33, 0xffffffb7, v32
	s_nop 0
	v_cndmask_b32_e32 v28, v191, v28, vcc
	v_cmp_lt_u32_e32 vcc, s67, v33
	v_add_u32_e32 v33, 0xffffff98, v32
	s_nop 0
	v_cndmask_b32_e32 v12, v191, v12, vcc
	v_cmp_lt_u32_e32 vcc, s67, v33
	v_add_u32_e32 v33, 0xffffffb8, v32
	s_nop 0
	v_cndmask_b32_e32 v29, v191, v29, vcc
	v_cmp_lt_u32_e32 vcc, s67, v33
	v_add_u32_e32 v33, 0xffffff99, v32
	s_nop 0
	v_cndmask_b32_e32 v13, v191, v13, vcc
	v_cmp_lt_u32_e32 vcc, s67, v33
	v_add_u32_e32 v33, 0xffffffb9, v32
	s_nop 0
	v_cndmask_b32_e32 v30, v191, v30, vcc
	v_cmp_lt_u32_e32 vcc, s67, v33
	v_add_u32_e32 v33, 0xffffff9a, v32
	v_add_u32_e32 v32, 0xffffffba, v32
	v_cndmask_b32_e32 v14, v191, v14, vcc
	v_cmp_lt_u32_e32 vcc, s67, v33
	s_nop 1
	v_cndmask_b32_e32 v31, v191, v31, vcc
	v_cmp_lt_u32_e32 vcc, s67, v32
	s_nop 1
	v_cndmask_b32_e32 v15, v191, v15, vcc

.Lepi16_w:
	v_lshl_add_u32 v88, v194, 4, v113
	ds_read_b128 v[80:83], v88
	ds_read_b128 v[84:87], v88 offset:32
	ds_read_b128 v[92:95], v88 offset:64
	ds_read_b128 v[96:99], v88 offset:96
	v_mov_b32_e32 v165, v163
	s_waitcnt lgkmcnt(0)
	v_add_f32_e32 v64, v64, v80
	v_add_f32_e32 v65, v65, v81
	v_add_f32_e32 v66, v66, v82
	v_add_f32_e32 v67, v67, v83
	v_add_f32_e32 v68, v68, v84
	v_add_f32_e32 v69, v69, v85
	v_add_f32_e32 v70, v70, v86
	v_add_f32_e32 v71, v71, v87
	v_add_f32_e32 v72, v72, v92
	v_add_f32_e32 v73, v73, v93
	v_add_f32_e32 v74, v74, v94
	v_add_f32_e32 v75, v75, v95
	v_add_f32_e32 v76, v76, v96
	v_add_f32_e32 v77, v77, v97
	v_add_f32_e32 v78, v78, v98
	v_add_f32_e32 v79, v79, v99
	v_lshlrev_b64 v[84:85], 12, v[164:165]
	v_lshl_or_b32 v82, v194, 13, v193
	v_mov_b32_e32 v83, v163
	v_lshl_add_u64 v[86:87], s[86:87], 0, v[84:85]
	v_lshl_add_u64 v[84:85], s[88:89], 0, v[84:85]
	v_lshlrev_b32_e32 v80, 1, v82
	v_mov_b32_e32 v81, v163
	v_lshl_add_u64 v[84:85], v[84:85], 0, v[80:81]
	v_lshl_add_u64 v[86:87], v[86:87], 0, v[80:81]
	s_mov_b64 s[4:5], 0x1000
	v_lshl_add_u64 v[88:89], v[84:85], 0, s[4:5]
	global_load_ushort v94, v[88:89], off offset:-4096 nt
	global_load_ushort v95, v[88:89], off offset:-4032 nt
	global_load_ushort v96, v[88:89], off offset:-3968 nt
	global_load_ushort v97, v[88:89], off offset:-3904 nt
	global_load_ushort v98, v[88:89], off nt
	global_load_ushort v99, v[88:89], off offset:64 nt
	global_load_ushort v100, v[88:89], off offset:128 nt
	global_load_ushort v101, v[88:89], off offset:192 nt
	s_mov_b64 s[4:5], 0x3000
	v_lshl_add_u64 v[90:91], v[84:85], 0, s[4:5]
	global_load_ushort v102, v[90:91], off offset:-4096 nt
	global_load_ushort v103, v[90:91], off offset:-4032 nt
	global_load_ushort v104, v[90:91], off offset:-3968 nt
	global_load_ushort v105, v[90:91], off offset:-3904 nt
	global_load_ushort v106, v[90:91], off nt
	global_load_ushort v107, v[90:91], off offset:64 nt
	global_load_ushort v108, v[90:91], off offset:128 nt
	global_load_ushort v109, v[90:91], off offset:192 nt
	s_mov_b64 s[4:5], 0x9000
	v_lshl_add_u64 v[88:89], v[84:85], 0, s[4:5]
	global_load_ushort v110, v[88:89], off offset:-4096 nt
	global_load_ushort v111, v[88:89], off offset:-4032 nt
	global_load_ushort v114, v[88:89], off offset:-3968 nt
	global_load_ushort v115, v[88:89], off offset:-3904 nt
	global_load_ushort v116, v[88:89], off nt
	global_load_ushort v117, v[88:89], off offset:64 nt
	global_load_ushort v118, v[88:89], off offset:128 nt
	global_load_ushort v119, v[88:89], off offset:192 nt
	s_mov_b64 s[4:5], 0xb000
	v_lshl_add_u64 v[90:91], v[84:85], 0, s[4:5]
	global_load_ushort v120, v[90:91], off offset:-4096 nt
	global_load_ushort v121, v[90:91], off offset:-4032 nt
	global_load_ushort v122, v[90:91], off offset:-3968 nt
	global_load_ushort v123, v[90:91], off offset:-3904 nt
	global_load_ushort v124, v[90:91], off nt
	global_load_ushort v125, v[90:91], off offset:64 nt
	global_load_ushort v126, v[90:91], off offset:128 nt
	global_load_ushort v127, v[90:91], off offset:192 nt
	v_mul_f32_e32 v64, 0x41800000, v64
	v_mul_f32_e32 v65, 0x41800000, v65
	v_mul_f32_e32 v66, 0x41800000, v66
	v_mul_f32_e32 v67, 0x41800000, v67
	v_mul_f32_e32 v68, 0x41800000, v68
	v_mul_f32_e32 v69, 0x41800000, v69
	v_mul_f32_e32 v70, 0x41800000, v70
	v_mul_f32_e32 v71, 0x41800000, v71
	v_mul_f32_e32 v72, 0x41800000, v72
	v_mul_f32_e32 v73, 0x41800000, v73
	v_mul_f32_e32 v74, 0x41800000, v74
	v_mul_f32_e32 v75, 0x41800000, v75
	v_mul_f32_e32 v76, 0x41800000, v76
	v_mul_f32_e32 v77, 0x41800000, v77
	v_mul_f32_e32 v78, 0x41800000, v78
	v_mul_f32_e32 v79, 0x41800000, v79
	v_rcp_f32_e32 v64, v64
	v_rcp_f32_e32 v65, v65
	v_rcp_f32_e32 v66, v66
	v_rcp_f32_e32 v67, v67
	v_rcp_f32_e32 v68, v68
	v_rcp_f32_e32 v69, v69
	v_rcp_f32_e32 v70, v70
	v_rcp_f32_e32 v71, v71
	v_rcp_f32_e32 v72, v72
	v_rcp_f32_e32 v73, v73
	v_rcp_f32_e32 v74, v74
	v_rcp_f32_e32 v75, v75
	v_rcp_f32_e32 v76, v76
	v_rcp_f32_e32 v77, v77
	v_rcp_f32_e32 v78, v78
	v_rcp_f32_e32 v79, v79
	v_mul_f32_e32 v48, v48, v64
	v_mul_f32_e32 v32, v32, v64
	v_mul_f32_e32 v16, v16, v64
	v_mul_f32_e32 v0, v0, v64
	v_mul_f32_e32 v49, v49, v65
	v_mul_f32_e32 v33, v33, v65
	v_mul_f32_e32 v17, v17, v65
	v_mul_f32_e32 v1, v1, v65
	v_mul_f32_e32 v50, v50, v66
	v_mul_f32_e32 v34, v34, v66
	v_mul_f32_e32 v18, v18, v66
	v_mul_f32_e32 v2, v2, v66
	v_mul_f32_e32 v51, v51, v67
	v_mul_f32_e32 v35, v35, v67
	v_mul_f32_e32 v19, v19, v67
	v_mul_f32_e32 v3, v3, v67
	v_mul_f32_e32 v52, v52, v68
	v_mul_f32_e32 v36, v36, v68
	v_mul_f32_e32 v20, v20, v68
	v_mul_f32_e32 v4, v4, v68
	v_mul_f32_e32 v53, v53, v69
	v_mul_f32_e32 v37, v37, v69
	v_mul_f32_e32 v21, v21, v69
	v_mul_f32_e32 v5, v5, v69
	v_mul_f32_e32 v54, v54, v70
	v_mul_f32_e32 v38, v38, v70
	v_mul_f32_e32 v22, v22, v70
	v_mul_f32_e32 v6, v6, v70
	v_mul_f32_e32 v55, v55, v71
	v_mul_f32_e32 v39, v39, v71
	v_mul_f32_e32 v23, v23, v71
	v_mul_f32_e32 v7, v7, v71
	v_mul_f32_e32 v56, v56, v72
	v_mul_f32_e32 v40, v40, v72
	v_mul_f32_e32 v24, v24, v72
	v_mul_f32_e32 v8, v8, v72
	v_mul_f32_e32 v57, v57, v73
	v_mul_f32_e32 v41, v41, v73
	v_mul_f32_e32 v25, v25, v73
	v_mul_f32_e32 v9, v9, v73
	v_mul_f32_e32 v58, v58, v74
	v_mul_f32_e32 v42, v42, v74
	v_mul_f32_e32 v26, v26, v74
	v_mul_f32_e32 v10, v10, v74
	v_mul_f32_e32 v59, v59, v75
	v_mul_f32_e32 v43, v43, v75
	v_mul_f32_e32 v27, v27, v75
	v_mul_f32_e32 v11, v11, v75
	v_mul_f32_e32 v60, v60, v76
	v_mul_f32_e32 v44, v44, v76
	v_mul_f32_e32 v28, v28, v76
	v_mul_f32_e32 v12, v12, v76
	v_mul_f32_e32 v61, v61, v77
	v_mul_f32_e32 v45, v45, v77
	v_mul_f32_e32 v29, v29, v77
	v_mul_f32_e32 v13, v13, v77
	v_mul_f32_e32 v62, v62, v78
	v_mul_f32_e32 v46, v46, v78
	v_mul_f32_e32 v30, v30, v78
	v_mul_f32_e32 v14, v14, v78
	v_mul_f32_e32 v63, v63, v79
	v_mul_f32_e32 v47, v47, v79
	v_mul_f32_e32 v31, v31, v79
	v_mul_f32_e32 v15, v15, v79
	s_waitcnt vmcnt(16)
	s_mov_b64 s[4:5], 0x1000
	v_lshl_add_u64 v[80:81], v[86:87], 0, s[4:5]
	s_mov_b64 s[4:5], 0x3000
	v_lshl_add_u64 v[92:93], v[86:87], 0, s[4:5]
	v_lshlrev_b32_e32 v94, 16, v94
	v_mul_f32_e32 v94, v48, v94
	v_cvt_pk_bf16_f32 v94, v94, v94
	global_store_short v[80:81], v94, off offset:-4096
	v_lshlrev_b32_e32 v95, 16, v95
	v_mul_f32_e32 v95, v32, v95
	v_cvt_pk_bf16_f32 v95, v95, v95
	global_store_short v[80:81], v95, off offset:-4032
	v_lshlrev_b32_e32 v96, 16, v96
	v_mul_f32_e32 v96, v16, v96
	v_cvt_pk_bf16_f32 v96, v96, v96
	global_store_short v[80:81], v96, off offset:-3968
	v_lshlrev_b32_e32 v97, 16, v97
	v_mul_f32_e32 v97, v0, v97
	v_cvt_pk_bf16_f32 v97, v97, v97
	global_store_short v[80:81], v97, off offset:-3904
	v_lshlrev_b32_e32 v98, 16, v98
	v_mul_f32_e32 v98, v49, v98
	v_cvt_pk_bf16_f32 v98, v98, v98
	global_store_short v[80:81], v98, off
	v_lshlrev_b32_e32 v99, 16, v99
	v_mul_f32_e32 v99, v33, v99
	v_cvt_pk_bf16_f32 v99, v99, v99
	global_store_short v[80:81], v99, off offset:64
	v_lshlrev_b32_e32 v100, 16, v100
	v_mul_f32_e32 v100, v17, v100
	v_cvt_pk_bf16_f32 v100, v100, v100
	global_store_short v[80:81], v100, off offset:128
	v_lshlrev_b32_e32 v101, 16, v101
	v_mul_f32_e32 v101, v1, v101
	v_cvt_pk_bf16_f32 v101, v101, v101
	global_store_short v[80:81], v101, off offset:192
	v_lshlrev_b32_e32 v102, 16, v102
	v_mul_f32_e32 v102, v50, v102
	v_cvt_pk_bf16_f32 v102, v102, v102
	global_store_short v[92:93], v102, off offset:-4096
	v_lshlrev_b32_e32 v103, 16, v103
	v_mul_f32_e32 v103, v34, v103
	v_cvt_pk_bf16_f32 v103, v103, v103
	global_store_short v[92:93], v103, off offset:-4032
	v_lshlrev_b32_e32 v104, 16, v104
	v_mul_f32_e32 v104, v18, v104
	v_cvt_pk_bf16_f32 v104, v104, v104
	global_store_short v[92:93], v104, off offset:-3968
	v_lshlrev_b32_e32 v105, 16, v105
	v_mul_f32_e32 v105, v2, v105
	v_cvt_pk_bf16_f32 v105, v105, v105
	global_store_short v[92:93], v105, off offset:-3904
	v_lshlrev_b32_e32 v106, 16, v106
	v_mul_f32_e32 v106, v51, v106
	v_cvt_pk_bf16_f32 v106, v106, v106
	global_store_short v[92:93], v106, off
	v_lshlrev_b32_e32 v107, 16, v107
	v_mul_f32_e32 v107, v35, v107
	v_cvt_pk_bf16_f32 v107, v107, v107
	global_store_short v[92:93], v107, off offset:64
	v_lshlrev_b32_e32 v108, 16, v108
	v_mul_f32_e32 v108, v19, v108
	v_cvt_pk_bf16_f32 v108, v108, v108
	global_store_short v[92:93], v108, off offset:128
	v_lshlrev_b32_e32 v109, 16, v109
	v_mul_f32_e32 v109, v3, v109
	v_cvt_pk_bf16_f32 v109, v109, v109
	global_store_short v[92:93], v109, off offset:192
	s_mov_b64 s[4:5], 0x11000
	v_lshl_add_u64 v[88:89], v[84:85], 0, s[4:5]
	global_load_ushort v128, v[88:89], off offset:-4096 nt
	global_load_ushort v129, v[88:89], off offset:-4032 nt
	global_load_ushort v130, v[88:89], off offset:-3968 nt
	global_load_ushort v131, v[88:89], off offset:-3904 nt
	global_load_ushort v132, v[88:89], off nt
	global_load_ushort v133, v[88:89], off offset:64 nt
	global_load_ushort v134, v[88:89], off offset:128 nt
	global_load_ushort v135, v[88:89], off offset:192 nt
	s_mov_b64 s[4:5], 0x13000
	v_lshl_add_u64 v[90:91], v[84:85], 0, s[4:5]
	global_load_ushort v136, v[90:91], off offset:-4096 nt
	global_load_ushort v137, v[90:91], off offset:-4032 nt
	global_load_ushort v138, v[90:91], off offset:-3968 nt
	global_load_ushort v139, v[90:91], off offset:-3904 nt
	global_load_ushort v140, v[90:91], off nt
	global_load_ushort v141, v[90:91], off offset:64 nt
	global_load_ushort v142, v[90:91], off offset:128 nt
	global_load_ushort v143, v[90:91], off offset:192 nt
	s_waitcnt vmcnt(32)
	s_mov_b64 s[4:5], 0x9000
	v_lshl_add_u64 v[80:81], v[86:87], 0, s[4:5]
	s_mov_b64 s[4:5], 0xb000
	v_lshl_add_u64 v[92:93], v[86:87], 0, s[4:5]
	v_lshlrev_b32_e32 v110, 16, v110
	v_mul_f32_e32 v110, v52, v110
	v_cvt_pk_bf16_f32 v110, v110, v110
	global_store_short v[80:81], v110, off offset:-4096
	v_lshlrev_b32_e32 v111, 16, v111
	v_mul_f32_e32 v111, v36, v111
	v_cvt_pk_bf16_f32 v111, v111, v111
	global_store_short v[80:81], v111, off offset:-4032
	v_lshlrev_b32_e32 v114, 16, v114
	v_mul_f32_e32 v114, v20, v114
	v_cvt_pk_bf16_f32 v114, v114, v114
	global_store_short v[80:81], v114, off offset:-3968
	v_lshlrev_b32_e32 v115, 16, v115
	v_mul_f32_e32 v115, v4, v115
	v_cvt_pk_bf16_f32 v115, v115, v115
	global_store_short v[80:81], v115, off offset:-3904
	v_lshlrev_b32_e32 v116, 16, v116
	v_mul_f32_e32 v116, v53, v116
	v_cvt_pk_bf16_f32 v116, v116, v116
	global_store_short v[80:81], v116, off
	v_lshlrev_b32_e32 v117, 16, v117
	v_mul_f32_e32 v117, v37, v117
	v_cvt_pk_bf16_f32 v117, v117, v117
	global_store_short v[80:81], v117, off offset:64
	v_lshlrev_b32_e32 v118, 16, v118
	v_mul_f32_e32 v118, v21, v118
	v_cvt_pk_bf16_f32 v118, v118, v118
	global_store_short v[80:81], v118, off offset:128
	v_lshlrev_b32_e32 v119, 16, v119
	v_mul_f32_e32 v119, v5, v119
	v_cvt_pk_bf16_f32 v119, v119, v119
	global_store_short v[80:81], v119, off offset:192
	v_lshlrev_b32_e32 v120, 16, v120
	v_mul_f32_e32 v120, v54, v120
	v_cvt_pk_bf16_f32 v120, v120, v120
	global_store_short v[92:93], v120, off offset:-4096
	v_lshlrev_b32_e32 v121, 16, v121
	v_mul_f32_e32 v121, v38, v121
	v_cvt_pk_bf16_f32 v121, v121, v121
	global_store_short v[92:93], v121, off offset:-4032
	v_lshlrev_b32_e32 v122, 16, v122
	v_mul_f32_e32 v122, v22, v122
	v_cvt_pk_bf16_f32 v122, v122, v122
	global_store_short v[92:93], v122, off offset:-3968
	v_lshlrev_b32_e32 v123, 16, v123
	v_mul_f32_e32 v123, v6, v123
	v_cvt_pk_bf16_f32 v123, v123, v123
	global_store_short v[92:93], v123, off offset:-3904
	v_lshlrev_b32_e32 v124, 16, v124
	v_mul_f32_e32 v124, v55, v124
	v_cvt_pk_bf16_f32 v124, v124, v124
	global_store_short v[92:93], v124, off
	v_lshlrev_b32_e32 v125, 16, v125
	v_mul_f32_e32 v125, v39, v125
	v_cvt_pk_bf16_f32 v125, v125, v125
	global_store_short v[92:93], v125, off offset:64
	v_lshlrev_b32_e32 v126, 16, v126
	v_mul_f32_e32 v126, v23, v126
	v_cvt_pk_bf16_f32 v126, v126, v126
	global_store_short v[92:93], v126, off offset:128
	v_lshlrev_b32_e32 v127, 16, v127
	v_mul_f32_e32 v127, v7, v127
	v_cvt_pk_bf16_f32 v127, v127, v127
	global_store_short v[92:93], v127, off offset:192
	s_waitcnt vmcnt(32)
	s_mov_b64 s[4:5], 0x19000
	v_lshl_add_u64 v[88:89], v[84:85], 0, s[4:5]
	global_load_ushort v144, v[88:89], off offset:-4096 nt
	global_load_ushort v145, v[88:89], off offset:-4032 nt
	global_load_ushort v146, v[88:89], off offset:-3968 nt
	global_load_ushort v147, v[88:89], off offset:-3904 nt
	global_load_ushort v148, v[88:89], off nt
	global_load_ushort v149, v[88:89], off offset:64 nt
	global_load_ushort v150, v[88:89], off offset:128 nt
	global_load_ushort v151, v[88:89], off offset:192 nt
	s_mov_b64 s[4:5], 0x1b000
	v_lshl_add_u64 v[90:91], v[84:85], 0, s[4:5]
	global_load_ushort v152, v[90:91], off offset:-4096 nt
	global_load_ushort v153, v[90:91], off offset:-4032 nt
	global_load_ushort v154, v[90:91], off offset:-3968 nt
	global_load_ushort v155, v[90:91], off offset:-3904 nt
	global_load_ushort v156, v[90:91], off nt
	global_load_ushort v157, v[90:91], off offset:64 nt
	global_load_ushort v158, v[90:91], off offset:128 nt
	global_load_ushort v159, v[90:91], off offset:192 nt
	s_waitcnt vmcnt(32)
	s_mov_b64 s[4:5], 0x11000
	v_lshl_add_u64 v[80:81], v[86:87], 0, s[4:5]
	s_mov_b64 s[4:5], 0x13000
	v_lshl_add_u64 v[92:93], v[86:87], 0, s[4:5]
	v_lshlrev_b32_e32 v128, 16, v128
	v_mul_f32_e32 v128, v56, v128
	v_cvt_pk_bf16_f32 v128, v128, v128
	global_store_short v[80:81], v128, off offset:-4096
	v_lshlrev_b32_e32 v129, 16, v129
	v_mul_f32_e32 v129, v40, v129
	v_cvt_pk_bf16_f32 v129, v129, v129
	global_store_short v[80:81], v129, off offset:-4032
	v_lshlrev_b32_e32 v130, 16, v130
	v_mul_f32_e32 v130, v24, v130
	v_cvt_pk_bf16_f32 v130, v130, v130
	global_store_short v[80:81], v130, off offset:-3968
	v_lshlrev_b32_e32 v131, 16, v131
	v_mul_f32_e32 v131, v8, v131
	v_cvt_pk_bf16_f32 v131, v131, v131
	global_store_short v[80:81], v131, off offset:-3904
	v_lshlrev_b32_e32 v132, 16, v132
	v_mul_f32_e32 v132, v57, v132
	v_cvt_pk_bf16_f32 v132, v132, v132
	global_store_short v[80:81], v132, off
	v_lshlrev_b32_e32 v133, 16, v133
	v_mul_f32_e32 v133, v41, v133
	v_cvt_pk_bf16_f32 v133, v133, v133
	global_store_short v[80:81], v133, off offset:64
	v_lshlrev_b32_e32 v134, 16, v134
	v_mul_f32_e32 v134, v25, v134
	v_cvt_pk_bf16_f32 v134, v134, v134
	global_store_short v[80:81], v134, off offset:128
	v_lshlrev_b32_e32 v135, 16, v135
	v_mul_f32_e32 v135, v9, v135
	v_cvt_pk_bf16_f32 v135, v135, v135
	global_store_short v[80:81], v135, off offset:192
	v_lshlrev_b32_e32 v136, 16, v136
	v_mul_f32_e32 v136, v58, v136
	v_cvt_pk_bf16_f32 v136, v136, v136
	global_store_short v[92:93], v136, off offset:-4096
	v_lshlrev_b32_e32 v137, 16, v137
	v_mul_f32_e32 v137, v42, v137
	v_cvt_pk_bf16_f32 v137, v137, v137
	global_store_short v[92:93], v137, off offset:-4032
	v_lshlrev_b32_e32 v138, 16, v138
	v_mul_f32_e32 v138, v26, v138
	v_cvt_pk_bf16_f32 v138, v138, v138
	global_store_short v[92:93], v138, off offset:-3968
	v_lshlrev_b32_e32 v139, 16, v139
	v_mul_f32_e32 v139, v10, v139
	v_cvt_pk_bf16_f32 v139, v139, v139
	global_store_short v[92:93], v139, off offset:-3904
	v_lshlrev_b32_e32 v140, 16, v140
	v_mul_f32_e32 v140, v59, v140
	v_cvt_pk_bf16_f32 v140, v140, v140
	global_store_short v[92:93], v140, off
	v_lshlrev_b32_e32 v141, 16, v141
	v_mul_f32_e32 v141, v43, v141
	v_cvt_pk_bf16_f32 v141, v141, v141
	global_store_short v[92:93], v141, off offset:64
	v_lshlrev_b32_e32 v142, 16, v142
	v_mul_f32_e32 v142, v27, v142
	v_cvt_pk_bf16_f32 v142, v142, v142
	global_store_short v[92:93], v142, off offset:128
	v_lshlrev_b32_e32 v143, 16, v143
	v_mul_f32_e32 v143, v11, v143
	v_cvt_pk_bf16_f32 v143, v143, v143
	global_store_short v[92:93], v143, off offset:192
	s_waitcnt vmcnt(16)
	s_mov_b64 s[4:5], 0x19000
	v_lshl_add_u64 v[80:81], v[86:87], 0, s[4:5]
	s_mov_b64 s[4:5], 0x1b000
	v_lshl_add_u64 v[92:93], v[86:87], 0, s[4:5]
	v_lshlrev_b32_e32 v144, 16, v144
	v_mul_f32_e32 v144, v60, v144
	v_cvt_pk_bf16_f32 v144, v144, v144
	global_store_short v[80:81], v144, off offset:-4096
	v_lshlrev_b32_e32 v145, 16, v145
	v_mul_f32_e32 v145, v44, v145
	v_cvt_pk_bf16_f32 v145, v145, v145
	global_store_short v[80:81], v145, off offset:-4032
	v_lshlrev_b32_e32 v146, 16, v146
	v_mul_f32_e32 v146, v28, v146
	v_cvt_pk_bf16_f32 v146, v146, v146
	global_store_short v[80:81], v146, off offset:-3968
	v_lshlrev_b32_e32 v147, 16, v147
	v_mul_f32_e32 v147, v12, v147
	v_cvt_pk_bf16_f32 v147, v147, v147
	global_store_short v[80:81], v147, off offset:-3904
	v_lshlrev_b32_e32 v148, 16, v148
	v_mul_f32_e32 v148, v61, v148
	v_cvt_pk_bf16_f32 v148, v148, v148
	global_store_short v[80:81], v148, off
	v_lshlrev_b32_e32 v149, 16, v149
	v_mul_f32_e32 v149, v45, v149
	v_cvt_pk_bf16_f32 v149, v149, v149
	global_store_short v[80:81], v149, off offset:64
	v_lshlrev_b32_e32 v150, 16, v150
	v_mul_f32_e32 v150, v29, v150
	v_cvt_pk_bf16_f32 v150, v150, v150
	global_store_short v[80:81], v150, off offset:128
	v_lshlrev_b32_e32 v151, 16, v151
	v_mul_f32_e32 v151, v13, v151
	v_cvt_pk_bf16_f32 v151, v151, v151
	global_store_short v[80:81], v151, off offset:192
	v_lshlrev_b32_e32 v152, 16, v152
	v_mul_f32_e32 v152, v62, v152
	v_cvt_pk_bf16_f32 v152, v152, v152
	global_store_short v[92:93], v152, off offset:-4096
	v_lshlrev_b32_e32 v153, 16, v153
	v_mul_f32_e32 v153, v46, v153
	v_cvt_pk_bf16_f32 v153, v153, v153
	global_store_short v[92:93], v153, off offset:-4032
	v_lshlrev_b32_e32 v154, 16, v154
	v_mul_f32_e32 v154, v30, v154
	v_cvt_pk_bf16_f32 v154, v154, v154
	global_store_short v[92:93], v154, off offset:-3968
	v_lshlrev_b32_e32 v155, 16, v155
	v_mul_f32_e32 v155, v14, v155
	v_cvt_pk_bf16_f32 v155, v155, v155
	global_store_short v[92:93], v155, off offset:-3904
	v_lshlrev_b32_e32 v156, 16, v156
	v_mul_f32_e32 v156, v63, v156
	v_cvt_pk_bf16_f32 v156, v156, v156
	global_store_short v[92:93], v156, off
	v_lshlrev_b32_e32 v157, 16, v157
	v_mul_f32_e32 v157, v47, v157
	v_cvt_pk_bf16_f32 v157, v157, v157
	global_store_short v[92:93], v157, off offset:64
	v_lshlrev_b32_e32 v158, 16, v158
	v_mul_f32_e32 v158, v31, v158
	v_cvt_pk_bf16_f32 v158, v158, v158
	global_store_short v[92:93], v158, off offset:128
	v_lshlrev_b32_e32 v159, 16, v159
	v_mul_f32_e32 v159, v15, v159
	v_cvt_pk_bf16_f32 v159, v159, v159
	global_store_short v[92:93], v159, off offset:192
	s_branch .LBB0_115

.LBB0_283:
	s_add_i32 s53, s53, 1
	s_mov_b64 s[4:5], 0
	s_barrier

.LBB0_292:
	s_cmpk_lt_i32 s14, 0x80
	s_cbranch_scc0 .LBB0_284
	s_mov_b32 s4, -1
	v_mbcnt_lo_u32_b32 v0, s4, 0
	v_mbcnt_hi_u32_b32 v0, s4, v0
	v_readlane_b32 s4, v255, 0
	s_nop 1
	v_or_b32_e32 v113, s4, v0
	s_ashr_i32 s4, s14, 31
	s_lshr_b32 s4, s4, 29
	s_add_i32 s15, s14, s4
	s_and_b32 s4, s15, -8
	s_sub_i32 s7, s14, s4
	s_cmp_gt_i32 s7, -1
	s_mov_b64 s[4:5], -1
	s_cbranch_scc0 .LBB0_295
	s_lshl_b32 s6, s7, 4
	s_mov_b64 s[4:5], 0

.LBB0_304:
	s_or_b64 exec, exec, s[4:5]
	s_waitcnt lgkmcnt(0)
	s_barrier
	global_load_dword v133, v[130:131], off
	global_load_dword v132, v[130:131], off offset:64
	v_add_u32_e32 v134, s64, v144
	ds_read_b128 v[228:231], v134
	s_lshl_b32 s4, s19, 7
	s_add_i32 s20, s4, 0xfffff000
	s_lshl_b32 s4, s18, 7
	s_add_i32 s18, s4, s14
	s_waitcnt lgkmcnt(0)
	v_add_f32_e32 v134, v228, v229
	v_add_f32_e32 v134, v230, v134
	v_add_f32_e32 v134, v231, v134
	v_fmamk_f32 v134, v134, 0x3c000000, v188
	v_rsq_f32_e32 v134, v134
	s_add_u32 s4, s74, s20
	s_addc_u32 s5, s75, 0
	s_lshl_b64 s[22:23], s[20:21], 2
	v_mul_f32_e32 v135, v225, v134
	v_mul_f32_e32 v134, v226, v134
	s_waitcnt vmcnt(1)
	v_mul_f32_e32 v135, v133, v135
	s_waitcnt vmcnt(0)
	v_mul_f32_e32 v134, v132, v134
	ds_write_b32 v142, v135
	ds_write_b32 v143, v134 offset:64
	v_add_u32_e32 v134, s64, v145
	ds_read_b128 v[226:229], v134
	s_waitcnt lgkmcnt(0)
	v_add_f32_e32 v134, v226, v227
	v_add_f32_e32 v134, v228, v134
	v_add_f32_e32 v134, v229, v134
	v_fmamk_f32 v134, v134, 0x3c000000, v188
	v_rsq_f32_e32 v134, v134
	s_nop 0
	v_mul_f32_e32 v135, v223, v134
	v_mul_f32_e32 v134, v224, v134
	v_mul_f32_e32 v135, v133, v135
	v_mul_f32_e32 v134, v132, v134
	ds_write_b32 v160, v135
	ds_write_b32 v161, v134 offset:64
	v_add_u32_e32 v134, s64, v146
	ds_read_b128 v[224:227], v134
	s_waitcnt lgkmcnt(0)
	v_add_f32_e32 v134, v224, v225
	v_add_f32_e32 v134, v226, v134
	v_add_f32_e32 v134, v227, v134
	v_fmamk_f32 v134, v134, 0x3c000000, v188
	v_rsq_f32_e32 v134, v134
	s_nop 0
	v_mul_f32_e32 v135, v221, v134
	v_mul_f32_e32 v134, v222, v134
	v_mul_f32_e32 v135, v133, v135
	v_mul_f32_e32 v134, v132, v134
	ds_write_b32 v164, v135
	ds_write_b32 v165, v134 offset:64
	v_add_u32_e32 v134, s64, v147
	ds_read_b128 v[222:225], v134
	s_waitcnt lgkmcnt(0)
	v_add_f32_e32 v134, v222, v223
	v_add_f32_e32 v134, v224, v134
	v_add_f32_e32 v134, v225, v134
	v_fmamk_f32 v134, v134, 0x3c000000, v188
	v_rsq_f32_e32 v134, v134
	s_nop 0
	v_mul_f32_e32 v135, v219, v134
	v_mul_f32_e32 v134, v220, v134
	v_mul_f32_e32 v135, v133, v135
	v_mul_f32_e32 v134, v132, v134
	ds_write_b32 v166, v135
	ds_write_b32 v167, v134 offset:64
	v_add_u32_e32 v134, s64, v148
	ds_read_b128 v[220:223], v134
	s_waitcnt lgkmcnt(0)
	v_add_f32_e32 v134, v220, v221
	v_add_f32_e32 v134, v222, v134
	v_add_f32_e32 v134, v223, v134
	v_fmamk_f32 v134, v134, 0x3c000000, v188
	v_rsq_f32_e32 v134, v134
	s_nop 0
	v_mul_f32_e32 v135, v217, v134
	v_mul_f32_e32 v134, v218, v134
	v_mul_f32_e32 v135, v133, v135
	v_mul_f32_e32 v134, v132, v134
	ds_write_b32 v168, v135
	ds_write_b32 v169, v134 offset:64
	v_add_u32_e32 v134, s64, v149
	ds_read_b128 v[218:221], v134
	s_waitcnt lgkmcnt(0)
	v_add_f32_e32 v134, v218, v219
	v_add_f32_e32 v134, v220, v134
	v_add_f32_e32 v134, v221, v134
	v_fmamk_f32 v134, v134, 0x3c000000, v188
	v_rsq_f32_e32 v134, v134
	s_nop 0
	v_mul_f32_e32 v135, v215, v134
	v_mul_f32_e32 v134, v216, v134
	v_mul_f32_e32 v135, v133, v135
	v_mul_f32_e32 v134, v132, v134
	ds_write_b32 v170, v135
	ds_write_b32 v171, v134 offset:64
	v_add_u32_e32 v134, s64, v150
	ds_read_b128 v[216:219], v134
	s_waitcnt lgkmcnt(0)
	v_add_f32_e32 v134, v216, v217
	v_add_f32_e32 v134, v218, v134
	v_add_f32_e32 v134, v219, v134
	v_fmamk_f32 v134, v134, 0x3c000000, v188
	v_rsq_f32_e32 v134, v134
	s_nop 0
	v_mul_f32_e32 v135, v213, v134
	v_mul_f32_e32 v134, v214, v134
	v_mul_f32_e32 v135, v133, v135
	v_mul_f32_e32 v134, v132, v134
	ds_write_b32 v172, v135
	ds_write_b32 v173, v134 offset:64
	v_add_u32_e32 v134, s64, v151
	ds_read_b128 v[214:217], v134
	s_waitcnt lgkmcnt(0)
	v_add_f32_e32 v134, v214, v215
	v_add_f32_e32 v134, v216, v134
	v_add_f32_e32 v134, v217, v134
	v_fmamk_f32 v134, v134, 0x3c000000, v188
	v_rsq_f32_e32 v134, v134
	s_nop 0
	v_mul_f32_e32 v135, v211, v134
	v_mul_f32_e32 v134, v212, v134
	v_mul_f32_e32 v135, v133, v135
	v_mul_f32_e32 v134, v132, v134
	ds_write_b32 v174, v135
	ds_write_b32 v175, v134 offset:64
	v_add_u32_e32 v134, s64, v152
	ds_read_b128 v[212:215], v134
	s_waitcnt lgkmcnt(0)
	v_add_f32_e32 v134, v212, v213
	v_add_f32_e32 v134, v214, v134
	v_add_f32_e32 v134, v215, v134
	v_fmamk_f32 v134, v134, 0x3c000000, v188
	v_rsq_f32_e32 v134, v134
	s_nop 0
	v_mul_f32_e32 v135, v209, v134
	v_mul_f32_e32 v134, v210, v134
	v_mul_f32_e32 v135, v133, v135
	v_mul_f32_e32 v134, v132, v134
	ds_write_b32 v176, v135
	ds_write_b32 v177, v134 offset:64
	v_add_u32_e32 v134, s64, v153
	ds_read_b128 v[210:213], v134
	s_waitcnt lgkmcnt(0)
	v_add_f32_e32 v134, v210, v211
	v_add_f32_e32 v134, v212, v134
	v_add_f32_e32 v134, v213, v134
	v_fmamk_f32 v134, v134, 0x3c000000, v188
	v_rsq_f32_e32 v134, v134
	s_nop 0
	v_mul_f32_e32 v135, v207, v134
	v_mul_f32_e32 v134, v208, v134
	v_mul_f32_e32 v135, v133, v135
	v_mul_f32_e32 v134, v132, v134
	ds_write_b32 v178, v135
	ds_write_b32 v179, v134 offset:64
	v_add_u32_e32 v134, s64, v154
	ds_read_b128 v[208:211], v134
	s_waitcnt lgkmcnt(0)
	v_add_f32_e32 v134, v208, v209
	v_add_f32_e32 v134, v210, v134
	v_add_f32_e32 v134, v211, v134
	v_fmamk_f32 v134, v134, 0x3c000000, v188
	v_rsq_f32_e32 v134, v134
	s_nop 0
	v_mul_f32_e32 v135, v205, v134
	v_mul_f32_e32 v134, v206, v134
	v_mul_f32_e32 v135, v133, v135
	v_mul_f32_e32 v134, v132, v134
	ds_write_b32 v180, v135
	ds_write_b32 v181, v134 offset:64
	v_add_u32_e32 v134, s64, v155
	ds_read_b128 v[206:209], v134
	s_waitcnt lgkmcnt(0)
	v_add_f32_e32 v134, v206, v207
	v_add_f32_e32 v134, v208, v134
	v_add_f32_e32 v134, v209, v134
	v_fmamk_f32 v134, v134, 0x3c000000, v188
	v_rsq_f32_e32 v134, v134
	s_nop 0
	v_mul_f32_e32 v135, v202, v134
	v_mul_f32_e32 v134, v203, v134
	v_mul_f32_e32 v135, v133, v135
	v_mul_f32_e32 v134, v132, v134
	ds_write_b32 v182, v135
	ds_write_b32 v183, v134 offset:64
	v_add_u32_e32 v134, s64, v156
	ds_read_b128 v[206:209], v134
	s_waitcnt lgkmcnt(0)
	v_add_f32_e32 v134, v206, v207
	v_add_f32_e32 v134, v208, v134
	v_add_f32_e32 v134, v209, v134
	v_fmamk_f32 v134, v134, 0x3c000000, v188
	v_rsq_f32_e32 v134, v134
	s_nop 0
	v_mul_f32_e32 v135, v200, v134
	v_mul_f32_e32 v134, v201, v134
	v_mul_f32_e32 v135, v133, v135
	v_mul_f32_e32 v134, v132, v134
	ds_write_b32 v184, v135
	ds_write_b32 v185, v134 offset:64
	v_add_u32_e32 v134, s64, v157
	ds_read_b128 v[200:203], v134
	s_waitcnt lgkmcnt(0)
	v_add_f32_e32 v134, v200, v201
	v_add_f32_e32 v134, v202, v134
	v_add_f32_e32 v134, v203, v134
	v_fmamk_f32 v134, v134, 0x3c000000, v188
	v_rsq_f32_e32 v134, v134
	s_nop 0
	v_mul_f32_e32 v135, v198, v134
	v_mul_f32_e32 v134, v199, v134
	v_mul_f32_e32 v135, v133, v135
	v_mul_f32_e32 v134, v132, v134
	ds_write_b32 v192, v135
	ds_write_b32 v193, v134 offset:64
	v_add_u32_e32 v134, s64, v158
	ds_read_b128 v[198:201], v134
	s_waitcnt lgkmcnt(0)
	v_add_f32_e32 v134, v198, v199
	v_add_f32_e32 v134, v200, v134
	v_add_f32_e32 v134, v201, v134
	v_fmamk_f32 v134, v134, 0x3c000000, v188
	v_rsq_f32_e32 v134, v134
	s_nop 0
	v_mul_f32_e32 v135, v138, v134
	v_mul_f32_e32 v134, v139, v134
	v_mul_f32_e32 v135, v133, v135
	v_mul_f32_e32 v134, v132, v134
	ds_write_b32 v194, v135
	ds_write_b32 v195, v134 offset:64
	v_add_u32_e32 v134, s64, v159
	ds_read_b128 v[198:201], v134
	v_lshlrev_b32_e32 v138, 2, v162
	v_mov_b32_e32 v139, v163
	s_waitcnt lgkmcnt(0)
	v_add_f32_e32 v134, v198, v199
	v_add_f32_e32 v134, v200, v134
	v_add_f32_e32 v134, v201, v134
	v_fmamk_f32 v134, v134, 0x3c000000, v188
	v_rsq_f32_e32 v134, v134
	s_nop 0
	v_mul_f32_e32 v135, v136, v134
	v_mul_f32_e32 v133, v133, v135
	ds_write_b32 v196, v133
	v_mul_f32_e32 v133, v137, v134
	v_add_u32_e32 v137, v204, v140
	v_mul_f32_e32 v132, v132, v133
	v_add_u32_e32 v136, s18, v137
	v_mul_lo_u32 v137, v137, s39
	ds_write_b32 v197, v132 offset:64
	v_lshl_add_u64 v[132:133], s[4:5], 0, v[162:163]
	v_lshl_add_u64 v[134:135], s[82:83], 0, v[138:139]
	v_add3_u32 v162, 0, v138, v137
	v_ashrrev_i32_e32 v138, 8, v136
	v_ashrrev_i32_e32 v139, 31, v138
	v_lshlrev_b64 v[138:139], 10, v[138:139]
	s_waitcnt lgkmcnt(0)
	s_barrier
	ds_read_b128 v[198:201], v162
	v_lshl_add_u64 v[138:139], v[138:139], 0, s[70:71]
	v_and_or_b32 v138, v136, s65, v138
	v_lshlrev_b64 v[138:139], 11, v[138:139]
	v_or_b32_e32 v139, s23, v139
	v_or_b32_e32 v138, s22, v138
	v_lshl_add_u64 v[138:139], v[134:135], 0, v[138:139]
	s_waitcnt lgkmcnt(0)
	global_store_dwordx4 v[138:139], v[198:201], off nt
	v_mul_f32_e32 v137, 0x41800000, v198
	v_mul_f32_e32 v138, 0x41800000, v199
	v_med3_f32 v137, v137, s66, v190
	v_med3_f32 v138, v138, s66, v190
	v_mov_b32_e32 v198, v163
	v_cvt_pk_fp8_f32 v198, v137, v138
	v_mul_f32_e32 v139, 0x41800000, v200
	v_mul_f32_e32 v187, 0x41800000, v201
	v_med3_f32 v137, v139, s66, v190
	v_med3_f32 v138, v187, s66, v190
	v_cvt_pk_fp8_f32 v198, v137, v138 op_sel:[0,0,1]
	v_ashrrev_i32_e32 v137, 31, v136
	v_lshlrev_b64 v[138:139], 9, v[136:137]
	v_lshl_add_u64 v[138:139], v[132:133], 0, v[138:139]
	global_store_dword v[138:139], v198, off
	v_add_u32_e32 v138, 2, v136
	v_ashrrev_i32_e32 v202, 8, v138
	v_ashrrev_i32_e32 v203, 31, v202
	ds_read_b128 v[198:201], v162 offset:1056
	v_lshlrev_b64 v[202:203], 10, v[202:203]
	v_lshl_add_u64 v[202:203], v[202:203], 0, s[70:71]
	v_and_or_b32 v202, v138, s65, v202
	v_lshlrev_b64 v[202:203], 11, v[202:203]
	v_or_b32_e32 v203, s23, v203
	v_or_b32_e32 v202, s22, v202
	v_lshl_add_u64 v[202:203], v[134:135], 0, v[202:203]
	s_waitcnt lgkmcnt(0)
	v_mul_f32_e32 v137, 0x41800000, v198
	v_mul_f32_e32 v139, 0x41800000, v199
	global_store_dwordx4 v[202:203], v[198:201], off nt
	v_med3_f32 v137, v137, s66, v190
	v_med3_f32 v139, v139, s66, v190
	v_mov_b32_e32 v199, v163
	v_cvt_pk_fp8_f32 v199, v137, v139
	v_mul_f32_e32 v187, 0x41800000, v200
	v_mul_f32_e32 v198, 0x41800000, v201
	v_med3_f32 v137, v187, s66, v190
	v_med3_f32 v139, v198, s66, v190
	v_cvt_pk_fp8_f32 v199, v137, v139 op_sel:[0,0,1]
	v_ashrrev_i32_e32 v139, 31, v138
	v_lshlrev_b64 v[138:139], 9, v[138:139]
	v_lshl_add_u64 v[138:139], v[132:133], 0, v[138:139]
	global_store_dword v[138:139], v199, off
	v_add_u32_e32 v138, 4, v136
	v_ashrrev_i32_e32 v202, 8, v138
	v_ashrrev_i32_e32 v203, 31, v202
	ds_read_b128 v[198:201], v162 offset:2112
	v_lshlrev_b64 v[202:203], 10, v[202:203]
	v_lshl_add_u64 v[202:203], v[202:203], 0, s[70:71]
	v_and_or_b32 v202, v138, s65, v202
	v_lshlrev_b64 v[202:203], 11, v[202:203]
	v_or_b32_e32 v203, s23, v203
	v_or_b32_e32 v202, s22, v202
	v_lshl_add_u64 v[202:203], v[134:135], 0, v[202:203]
	s_waitcnt lgkmcnt(0)
	v_mul_f32_e32 v137, 0x41800000, v198
	v_mul_f32_e32 v139, 0x41800000, v199
	global_store_dwordx4 v[202:203], v[198:201], off nt
	v_med3_f32 v137, v137, s66, v190
	v_med3_f32 v139, v139, s66, v190
	v_mov_b32_e32 v199, v163
	v_cvt_pk_fp8_f32 v199, v137, v139
	v_mul_f32_e32 v187, 0x41800000, v200
	v_mul_f32_e32 v198, 0x41800000, v201
	v_med3_f32 v137, v187, s66, v190
	v_med3_f32 v139, v198, s66, v190
	v_cvt_pk_fp8_f32 v199, v137, v139 op_sel:[0,0,1]
	v_ashrrev_i32_e32 v139, 31, v138
	v_lshlrev_b64 v[138:139], 9, v[138:139]
	v_lshl_add_u64 v[138:139], v[132:133], 0, v[138:139]
	global_store_dword v[138:139], v199, off
	v_add_u32_e32 v138, 6, v136
	v_ashrrev_i32_e32 v202, 8, v138
	v_ashrrev_i32_e32 v203, 31, v202
	ds_read_b128 v[198:201], v162 offset:3168
	v_lshlrev_b64 v[202:203], 10, v[202:203]
	v_lshl_add_u64 v[202:203], v[202:203], 0, s[70:71]
	v_and_or_b32 v202, v138, s65, v202
	v_lshlrev_b64 v[202:203], 11, v[202:203]
	v_or_b32_e32 v203, s23, v203
	v_or_b32_e32 v202, s22, v202
	v_lshl_add_u64 v[202:203], v[134:135], 0, v[202:203]
	s_waitcnt lgkmcnt(0)
	v_mul_f32_e32 v137, 0x41800000, v198
	v_mul_f32_e32 v139, 0x41800000, v199
	global_store_dwordx4 v[202:203], v[198:201], off nt
	v_med3_f32 v139, v139, s66, v190
	v_mul_f32_e32 v187, 0x41800000, v200
	v_med3_f32 v199, v137, s66, v190
	v_mov_b32_e32 v137, v163
	v_cvt_pk_fp8_f32 v137, v199, v139
	v_mul_f32_e32 v198, 0x41800000, v201
	v_med3_f32 v139, v187, s66, v190
	v_med3_f32 v187, v198, s66, v190
	v_cvt_pk_fp8_f32 v137, v139, v187 op_sel:[0,0,1]
	v_ashrrev_i32_e32 v139, 31, v138
	v_lshlrev_b64 v[138:139], 9, v[138:139]
	v_lshl_add_u64 v[138:139], v[132:133], 0, v[138:139]
	global_store_dword v[138:139], v137, off
	v_add_u32_e32 v138, 8, v136
	v_ashrrev_i32_e32 v202, 8, v138
	v_ashrrev_i32_e32 v203, 31, v202
	ds_read_b128 v[198:201], v162 offset:4224
	v_lshlrev_b64 v[202:203], 10, v[202:203]
	v_lshl_add_u64 v[202:203], v[202:203], 0, s[70:71]
	v_and_or_b32 v202, v138, s65, v202
	v_lshlrev_b64 v[202:203], 11, v[202:203]
	v_or_b32_e32 v203, s23, v203
	v_or_b32_e32 v202, s22, v202
	v_lshl_add_u64 v[202:203], v[134:135], 0, v[202:203]
	s_waitcnt lgkmcnt(0)
	v_mul_f32_e32 v137, 0x41800000, v198
	v_mul_f32_e32 v139, 0x41800000, v199
	global_store_dwordx4 v[202:203], v[198:201], off nt
	v_med3_f32 v137, v137, s66, v190
	v_med3_f32 v139, v139, s66, v190
	v_mov_b32_e32 v199, v163
	v_cvt_pk_fp8_f32 v199, v137, v139
	v_mul_f32_e32 v187, 0x41800000, v200
	v_mul_f32_e32 v198, 0x41800000, v201
	v_med3_f32 v137, v187, s66, v190
	v_med3_f32 v139, v198, s66, v190
	v_cvt_pk_fp8_f32 v199, v137, v139 op_sel:[0,0,1]
	v_ashrrev_i32_e32 v139, 31, v138
	v_lshlrev_b64 v[138:139], 9, v[138:139]
	v_lshl_add_u64 v[138:139], v[132:133], 0, v[138:139]
	global_store_dword v[138:139], v199, off
	v_add_u32_e32 v138, 10, v136
	v_ashrrev_i32_e32 v202, 8, v138
	v_ashrrev_i32_e32 v203, 31, v202
	ds_read_b128 v[198:201], v162 offset:5280
	v_lshlrev_b64 v[202:203], 10, v[202:203]
	v_lshl_add_u64 v[202:203], v[202:203], 0, s[70:71]
	v_and_or_b32 v202, v138, s65, v202
	v_lshlrev_b64 v[202:203], 11, v[202:203]
	v_or_b32_e32 v203, s23, v203
	v_or_b32_e32 v202, s22, v202
	v_lshl_add_u64 v[202:203], v[134:135], 0, v[202:203]
	s_waitcnt lgkmcnt(0)
	v_mul_f32_e32 v137, 0x41800000, v198
	v_mul_f32_e32 v139, 0x41800000, v199
	global_store_dwordx4 v[202:203], v[198:201], off nt
	v_med3_f32 v137, v137, s66, v190
	v_med3_f32 v139, v139, s66, v190
	v_mov_b32_e32 v199, v163
	v_cvt_pk_fp8_f32 v199, v137, v139
	v_mul_f32_e32 v187, 0x41800000, v200
	v_mul_f32_e32 v198, 0x41800000, v201
	v_med3_f32 v137, v187, s66, v190
	v_med3_f32 v139, v198, s66, v190
	v_cvt_pk_fp8_f32 v199, v137, v139 op_sel:[0,0,1]
	v_ashrrev_i32_e32 v139, 31, v138
	v_lshlrev_b64 v[138:139], 9, v[138:139]
	v_lshl_add_u64 v[138:139], v[132:133], 0, v[138:139]
	global_store_dword v[138:139], v199, off
	v_add_u32_e32 v138, 12, v136
	v_ashrrev_i32_e32 v202, 8, v138
	v_ashrrev_i32_e32 v203, 31, v202
	ds_read_b128 v[198:201], v162 offset:6336
	v_lshlrev_b64 v[202:203], 10, v[202:203]
	v_lshl_add_u64 v[202:203], v[202:203], 0, s[70:71]
	v_and_or_b32 v202, v138, s65, v202
	v_lshlrev_b64 v[202:203], 11, v[202:203]
	v_or_b32_e32 v203, s23, v203
	v_or_b32_e32 v202, s22, v202
	v_lshl_add_u64 v[202:203], v[134:135], 0, v[202:203]
	s_waitcnt lgkmcnt(0)
	v_mul_f32_e32 v137, 0x41800000, v198
	v_mul_f32_e32 v139, 0x41800000, v199
	global_store_dwordx4 v[202:203], v[198:201], off nt
	v_med3_f32 v137, v137, s66, v190
	v_med3_f32 v139, v139, s66, v190
	v_mov_b32_e32 v199, v163
	v_cvt_pk_fp8_f32 v199, v137, v139
	v_mul_f32_e32 v187, 0x41800000, v200
	v_mul_f32_e32 v198, 0x41800000, v201
	v_med3_f32 v137, v187, s66, v190
	v_med3_f32 v139, v198, s66, v190
	v_cvt_pk_fp8_f32 v199, v137, v139 op_sel:[0,0,1]
	v_add_u32_e32 v198, 14, v136
	v_ashrrev_i32_e32 v139, 31, v138
	v_ashrrev_i32_e32 v200, 8, v198
	v_lshlrev_b64 v[138:139], 9, v[138:139]
	v_ashrrev_i32_e32 v201, 31, v200
	v_lshl_add_u64 v[138:139], v[132:133], 0, v[138:139]
	v_lshlrev_b64 v[200:201], 10, v[200:201]
	global_store_dword v[138:139], v199, off
	ds_read_b128 v[136:139], v162 offset:7392
	v_lshl_add_u64 v[200:201], v[200:201], 0, s[70:71]
	v_and_or_b32 v200, v198, s65, v200
	v_lshlrev_b64 v[200:201], 11, v[200:201]
	v_or_b32_e32 v201, s23, v201
	v_or_b32_e32 v200, s22, v200
	v_lshl_add_u64 v[134:135], v[134:135], 0, v[200:201]
	s_waitcnt lgkmcnt(0)
	global_store_dwordx4 v[134:135], v[136:139], off nt
	v_mul_f32_e32 v134, 0x41800000, v136
	v_mul_f32_e32 v135, 0x41800000, v137
	v_mul_f32_e32 v136, 0x41800000, v138
	v_med3_f32 v134, v134, s66, v190
	v_med3_f32 v135, v135, s66, v190
	v_mov_b32_e32 v138, v163
	v_cvt_pk_fp8_f32 v138, v134, v135
	v_mul_f32_e32 v137, 0x41800000, v139
	v_med3_f32 v134, v136, s66, v190
	v_med3_f32 v135, v137, s66, v190
	v_cvt_pk_fp8_f32 v138, v134, v135 op_sel:[0,0,1]
	v_ashrrev_i32_e32 v199, 31, v198
	v_lshlrev_b64 v[134:135], 9, v[198:199]
	v_lshl_add_u64 v[132:133], v[132:133], 0, v[134:135]
	global_store_dword v[132:133], v138, off

.LBB0_316:
	v_and_b32_e32 v132, 63, v113
	s_and_b32 s4, s15, 1
	v_ashrrev_i32_e32 v204, 5, v132
	v_lshlrev_b32_e32 v132, 2, v132
	s_lshr_b32 s18, s15, 1
	v_and_b32_e32 v162, 0x7c, v132
	s_or_b32 s19, s4, s88
	s_mov_b64 s[4:5], -1
	s_and_b64 vcc, exec, s[80:81]
	s_cbranch_vccz .LBB0_324
	v_add_u32_e32 v132, 0x400, v142
	s_barrier
	ds_write2_b32 v142, v225, v223 offset1:132
	ds_write2_b32 v143, v226, v224 offset0:16 offset1:148
	ds_write2_b32 v132, v221, v219 offset0:8 offset1:140
	v_add_u32_e32 v132, 0x400, v143
	ds_write2_b32 v132, v222, v220 offset0:24 offset1:156
	v_add_u32_e32 v132, 0x2000, v142
	ds_write2_b32 v132, v217, v215 offset0:64 offset1:196
	v_add_u32_e32 v132, 0x2000, v143
	ds_write2_b32 v132, v218, v216 offset0:80 offset1:212
	v_add_u32_e32 v132, 0x2400, v142
	ds_write2_b32 v132, v213, v211 offset0:72 offset1:204
	v_add_u32_e32 v132, 0x2400, v143
	ds_write2_b32 v132, v214, v212 offset0:88 offset1:220
	v_add_u32_e32 v132, 0x4200, v142
	ds_write2_b32 v132, v209, v207 offset1:132
	v_add_u32_e32 v132, 0x4200, v143
	ds_write2_b32 v132, v210, v208 offset0:16 offset1:148
	v_add_u32_e32 v132, 0x4600, v142
	ds_write2_b32 v132, v205, v202 offset0:8 offset1:140
	v_add_u32_e32 v132, 0x4600, v143
	ds_write2_b32 v132, v206, v203 offset0:24 offset1:156
	v_add_u32_e32 v132, 0x6200, v142
	ds_write2_b32 v132, v200, v198 offset0:64 offset1:196
	v_add_u32_e32 v132, 0x6200, v143
	ds_write2_b32 v132, v201, v199 offset0:80 offset1:212
	v_add_u32_e32 v132, 0x6600, v142
	ds_write2_b32 v132, v138, v136 offset0:72 offset1:204
	v_add_u32_e32 v132, 0x6600, v143
	s_and_b64 vcc, exec, s[84:85]
	ds_write2_b32 v132, v139, v137 offset0:88 offset1:220
	s_waitcnt lgkmcnt(0)
	s_barrier
	s_cbranch_vccz .LBB0_321
	v_mov_b32_e32 v187, v113
	s_lshl_b32 s20, s18, 7
	s_sub_i32 s4, s19, 36
	s_add_i32 s20, s20, s14
	v_lshrrev_b32_e32 v133, 4, v187
	s_ashr_i32 s5, s4, 31
	v_xor_b32_e32 v134, v133, v187
	v_bitop3_b32 v133, v133, 2, v187 bitop3:0x48
	s_ashr_i32 s29, s20, 6
	s_lshl_b64 s[22:23], s[4:5], 13
	v_bfe_u32 v132, v187, 2, 7
	v_lshlrev_b32_e32 v134, 5, v134
	v_lshlrev_b32_e32 v133, 1, v133
	s_add_u32 s22, s78, s22
	v_bitop3_b32 v134, v133, 36, v134 bitop3:0xc8
	v_lshl_add_u32 v135, v132, 2, 0
	s_addc_u32 s23, s79, s23
	v_lshlrev_b32_e32 v132, 6, v132
	v_mov_b32_e32 v133, v163
	v_lshlrev_b32_e32 v187, 4, v187
	v_lshl_add_u64 v[132:133], s[22:23], 0, v[132:133]
	v_and_b32_e32 v228, 48, v187
	v_mov_b32_e32 v229, v163
	v_lshl_add_u64 v[132:133], v[132:133], 0, v[228:229]
	s_mov_b32 s33, 0
	s_mov_b64 s[22:23], -1

.LBB0_337:
	s_cmpk_lt_i32 s8, 0xc00
	s_cbranch_scc0 .LBB0_329
	s_mov_b32 s4, -1
	s_movk_i32 s7, 0xa0
	v_mbcnt_lo_u32_b32 v0, s4, 0
	v_mbcnt_hi_u32_b32 v0, s4, v0
	v_readlane_b32 s4, v255, 0
	s_nop 1
	v_or_b32_e32 v113, s4, v0
	s_add_i32 s4, s8, 0xfffff600
	s_cmpk_gt_i32 s8, 0x9ff
	s_cselect_b32 s7, 0x80, s7
	v_cvt_f32_ubyte0_e32 v0, s7
	s_cselect_b32 s4, s4, s8
	v_rcp_iflag_f32_e32 v0, v0
	s_cselect_b32 s5, 32, 0x80
	s_cselect_b32 s10, 0, 32
	s_cselect_b32 s6, 64, 0x140
	s_ashr_i32 s8, s4, 31
	s_lshr_b32 s8, s8, 29
	s_add_i32 s8, s4, s8
	s_ashr_i32 s9, s8, 3
	s_and_b32 s8, s8, -8
	v_mul_f32_e32 v0, 0x4f7ffffe, v0
	s_sub_i32 s4, s4, s8
	v_cvt_u32_f32_e32 v0, v0
	s_lshr_b32 s8, s4, 31
	s_or_b32 s6, s8, s6
	s_mul_i32 s4, s6, s4
	s_add_i32 s4, s4, s9
	s_sub_i32 s8, 0, s7
	v_readfirstlane_b32 s9, v0
	s_mul_i32 s8, s8, s9
	s_mul_hi_u32 s8, s9, s8
	s_abs_i32 s6, s4
	s_add_i32 s9, s9, s8
	s_mul_hi_u32 s8, s6, s9
	s_mul_i32 s9, s8, s7
	s_sub_i32 s6, s6, s9
	s_ashr_i32 s11, s4, 31
	s_add_i32 s9, s8, 1
	s_sub_i32 s12, s6, s7
	s_cmp_ge_u32 s6, s7
	s_cselect_b32 s8, s9, s8
	s_cselect_b32 s6, s12, s6
	s_add_i32 s9, s8, 1
	s_cmp_ge_u32 s6, s7
	s_cselect_b32 s6, s9, s8
	s_xor_b32 s12, s6, s11
	s_sub_i32 s6, s12, s11
	s_lshl_b32 s9, s6, 3
	s_sub_i32 s5, s5, s9
	s_min_i32 s13, s5, 8
	s_mul_i32 s6, s6, s7
	s_sub_i32 s6, s4, s6
	s_sext_i32_i16 s4, s13
	v_cvt_f32_i32_e32 v1, s4
	v_cvt_f32_i32_e32 v0, s6
	s_xor_b32 s5, s6, s4
	s_ashr_i32 s5, s5, 30
	v_rcp_iflag_f32_e32 v2, v1
	s_or_b32 s7, s5, 1
	v_lshlrev_b32_e32 v21, 4, v113
	v_mul_f32_e32 v2, v0, v2
	v_trunc_f32_e32 v2, v2
	v_fma_f32 v0, -v2, v1, v0
	v_cmp_ge_f32_e64 s[4:5], |v0|, |v1|
	v_ashrrev_i32_e32 v0, 31, v113
	v_lshrrev_b32_e32 v0, 26, v0
	v_add_u32_e32 v0, v113, v0
	v_ashrrev_i32_e32 v1, 6, v0
	v_bfe_i32 v0, v113, 27, 1
	v_cvt_i32_f32_e32 v2, v2
	v_lshrrev_b32_e32 v0, 22, v0
	v_add_u32_e32 v0, v21, v0
	v_and_b32_e32 v0, 0xfffffc00, v0
	s_and_b64 s[4:5], s[4:5], exec
	v_sub_u32_e32 v0, v21, v0
	v_readfirstlane_b32 s5, v2
	v_lshrrev_b32_e32 v2, 4, v0
	v_bitop3_b32 v2, v2, v0, 32 bitop3:0x6c
	v_ashrrev_i32_e32 v0, 31, v0
	s_cselect_b32 s4, s7, 0
	v_lshrrev_b32_e32 v0, 26, v0
	s_add_i32 s4, s5, s4
	v_lshlrev_b32_e32 v3, 3, v1
	v_add_u32_e32 v0, v2, v0
	s_sext_i32_i16 s8, s4
	s_mul_i32 s4, s4, s13
	v_and_b32_e32 v3, -16, v3
	v_ashrrev_i32_e32 v4, 6, v0
	v_lshlrev_b32_e32 v1, 5, v1
	s_sub_i32 s4, s6, s4
	s_lshl_b32 s6, s8, 8
	v_add_u32_e32 v0, v4, v3
	v_and_b32_e32 v3, 32, v1
	v_mul_i32_i24_e32 v1, 64, v4
	s_sext_i32_i16 s13, s4
	s_add_i32 s9, s9, s10
	s_ashr_i32 s7, s6, 31
	v_sub_u32_e32 v1, v2, v1
	s_add_i32 s9, s9, s13
	s_lshl_b64 s[4:5], s[6:7], 11
	v_ashrrev_i16_sdwa v1, v189, sext(v1) dst_sel:DWORD dst_unused:UNUSED_PAD src0_sel:DWORD src1_sel:BYTE_0
	s_add_u32 s18, s76, s4
	v_bfe_i32 v2, v1, 0, 16
	v_ashrrev_i32_e32 v1, 31, v0
	s_addc_u32 s19, s77, s5
	v_lshlrev_b64 v[0:1], 11, v[0:1]
	v_add_lshl_u32 v2, v3, v2, 1
	v_lshl_add_u64 v[4:5], s[18:19], 0, v[0:1]
	v_ashrrev_i32_e32 v3, 31, v2
	v_add_u32_e32 v22, 0x2000, v21
	v_lshl_add_u64 v[8:9], v[4:5], 0, v[2:3]
	v_ashrrev_i32_e32 v4, 31, v22
	v_lshrrev_b32_e32 v4, 22, v4
	v_add_u32_e32 v4, v22, v4
	v_ashrrev_i32_e32 v5, 10, v4
	v_mul_i32_i24_e32 v4, 0x400, v5
	v_sub_u32_e32 v4, v22, v4
	v_lshrrev_b32_e32 v6, 4, v4
	v_bitop3_b32 v6, v6, v4, 32 bitop3:0x6c
	v_ashrrev_i32_e32 v7, 31, v6
	v_lshrrev_b32_e32 v7, 26, v7
	v_lshlrev_b32_e32 v4, 3, v5
	v_add_u32_e32 v7, v6, v7
	v_lshlrev_b32_e32 v5, 5, v5
	v_and_b32_e32 v12, 32, v5
	v_and_b32_e32 v5, 0xc0, v7
	v_and_b32_e32 v4, -16, v4
	v_ashrrev_i32_e32 v10, 6, v7
	v_sub_u32_e32 v5, v6, v5
	v_add_u32_e32 v4, v10, v4
	v_ashrrev_i16_sdwa v5, v189, sext(v5) dst_sel:DWORD dst_unused:UNUSED_PAD src0_sel:DWORD src1_sel:BYTE_0
	v_bfe_i32 v6, v5, 0, 16
	v_ashrrev_i32_e32 v5, 31, v4
	s_lshl_b32 s78, s9, 8
	s_add_i32 s14, 0, 0x10000
	v_lshlrev_b64 v[4:5], 11, v[4:5]
	s_ashr_i32 s79, s78, 31
	v_add_u32_e32 v185, s14, v21
	v_lshl_add_u64 v[10:11], s[18:19], 0, v[4:5]
	s_lshl_b64 s[18:19], s[78:79], 11
	v_readfirstlane_b32 s7, v185
	v_add_lshl_u32 v6, v12, v6, 1
	v_add_u32_e32 v12, s14, v22
	s_add_u32 s18, s74, s18
	s_mov_b32 m0, s7
	v_ashrrev_i32_e32 v7, 31, v6
	v_readfirstlane_b32 s7, v12
	s_addc_u32 s19, s75, s19
	v_add_u32_e32 v192, 0, v21
	global_load_lds_dwordx4 v[8:9], off
	v_lshl_add_u64 v[10:11], v[10:11], 0, v[6:7]
	s_mov_b32 m0, s7
	v_lshl_add_u64 v[12:13], s[18:19], 0, v[0:1]
	v_readfirstlane_b32 s7, v192
	v_add_u32_e32 v193, 0x2000, v192
	global_load_lds_dwordx4 v[10:11], off
	v_lshl_add_u64 v[12:13], v[12:13], 0, v[2:3]
	s_mov_b32 m0, s7
	v_readfirstlane_b32 s7, v193
	s_bitset1_b32 s6, 7
	global_load_lds_dwordx4 v[12:13], off
	s_mov_b32 m0, s7
	s_ashr_i32 s7, s6, 31
	s_lshl_b64 s[6:7], s[6:7], 11
	s_add_u32 s6, s76, s6
	v_lshl_add_u64 v[14:15], s[18:19], 0, v[4:5]
	s_addc_u32 s7, s77, s7
	v_add_u32_e32 v194, s26, v21
	v_lshl_add_u64 v[14:15], v[14:15], 0, v[6:7]
	v_lshl_add_u64 v[16:17], s[6:7], 0, v[0:1]
	v_readfirstlane_b32 s15, v194
	v_add_u32_e32 v22, s26, v22
	global_load_lds_dwordx4 v[14:15], off
	v_lshl_add_u64 v[16:17], v[16:17], 0, v[2:3]
	s_mov_b32 m0, s15
	v_lshl_add_u64 v[18:19], s[6:7], 0, v[4:5]
	v_readfirstlane_b32 s6, v22
	global_load_lds_dwordx4 v[16:17], off
	s_mov_b32 m0, s6
	s_or_b32 s6, s78, 0x80
	s_ashr_i32 s7, s6, 31
	s_lshl_b64 s[6:7], s[6:7], 11
	s_add_u32 s6, s74, s6
	s_addc_u32 s7, s75, s7
	v_add_u32_e32 v195, 0x4000, v192
	v_lshl_add_u64 v[18:19], v[18:19], 0, v[6:7]
	v_lshl_add_u64 v[22:23], s[6:7], 0, v[0:1]
	v_readfirstlane_b32 s15, v195
	v_add_u32_e32 v196, 0x6000, v192
	global_load_lds_dwordx4 v[18:19], off
	v_lshl_add_u64 v[154:155], v[22:23], 0, v[2:3]
	s_mov_b32 m0, s15
	v_lshl_add_u64 v[22:23], s[6:7], 0, v[4:5]
	v_readfirstlane_b32 s6, v196
	global_load_lds_dwordx4 v[154:155], off
	v_lshl_add_u64 v[156:157], v[22:23], 0, v[6:7]
	s_mov_b32 m0, s6
	v_ashrrev_i32_e32 v20, 8, v113
	global_load_lds_dwordx4 v[156:157], off
	v_cmp_eq_u32_e32 vcc, 1, v20
	s_and_saveexec_b64 s[6:7], vcc
	s_cbranch_execz .LBB0_340
	s_barrier

.LBB0_358:
	s_and_b32 s4, s61, 1
	s_lshr_b32 s12, s61, 1
	s_or_b32 s33, s4, s79
	s_cmp_lt_i32 s33, 16
	v_mul_f32_e32 v222, 0x38800000, v6
	v_and_b32_e32 v6, 63, v113
	s_cselect_b64 s[14:15], -1, 0
	v_mul_f32_e32 v211, 0x38800000, v11
	s_or_b64 s[4:5], s[96:97], s[14:15]
	v_lshlrev_b32_e32 v11, 2, v6
	v_mul_f32_e32 v225, 0x38800000, v0
	v_mul_f32_e32 v223, 0x38800000, v1
	v_mul_f32_e32 v221, 0x38800000, v2
	v_mul_f32_e32 v219, 0x38800000, v3
	v_mul_f32_e32 v226, 0x38800000, v4
	v_mul_f32_e32 v224, 0x38800000, v5
	v_mul_f32_e32 v220, 0x38800000, v7
	v_mul_f32_e32 v217, 0x38800000, v8
	v_mul_f32_e32 v215, 0x38800000, v9
	v_mul_f32_e32 v213, 0x38800000, v10
	v_mul_f32_e32 v218, 0x38800000, v12
	v_mul_f32_e32 v216, 0x38800000, v13
	v_mul_f32_e32 v214, 0x38800000, v162
	v_mul_f32_e32 v212, 0x38800000, v203
	v_mul_f32_e32 v209, 0x38800000, v204
	v_mul_f32_e32 v207, 0x38800000, v205
	v_mul_f32_e32 v205, 0x38800000, v206
	v_mul_f32_e32 v203, 0x38800000, v208
	v_mul_f32_e32 v210, 0x38800000, v210
	v_mul_f32_e32 v208, 0x38800000, v227
	v_mul_f32_e32 v206, 0x38800000, v228
	v_mul_f32_e32 v204, 0x38800000, v229
	v_mul_f32_e32 v12, 0x38800000, v230
	v_mul_f32_e32 v7, 0x38800000, v231
	v_mul_f32_e32 v4, 0x38800000, v232
	v_mul_f32_e32 v2, 0x38800000, v233
	v_mul_f32_e32 v13, 0x38800000, v234
	v_mul_f32_e32 v9, 0x38800000, v235
	v_mul_f32_e32 v5, 0x38800000, v236
	v_mul_f32_e32 v3, 0x38800000, v237
	v_ashrrev_i32_e32 v10, 5, v6
	v_and_b32_e32 v8, 0x7c, v11
	s_andn2_b64 vcc, exec, s[4:5]
	s_mov_b64 s[4:5], -1
	s_cbranch_vccz .LBB0_368
	v_add_u32_e32 v0, 0x400, v16
	s_barrier
	ds_write2_b32 v16, v225, v223 offset1:132
	ds_write2_b32 v17, v226, v224 offset0:16 offset1:148
	ds_write2_b32 v0, v221, v219 offset0:8 offset1:140
	v_add_u32_e32 v0, 0x400, v17
	ds_write2_b32 v0, v222, v220 offset0:24 offset1:156
	v_add_u32_e32 v0, 0x2000, v16
	ds_write2_b32 v0, v217, v215 offset0:64 offset1:196
	v_add_u32_e32 v0, 0x2000, v17
	ds_write2_b32 v0, v218, v216 offset0:80 offset1:212
	v_add_u32_e32 v0, 0x2400, v16
	ds_write2_b32 v0, v213, v211 offset0:72 offset1:204
	v_add_u32_e32 v0, 0x2400, v17
	ds_write2_b32 v0, v214, v212 offset0:88 offset1:220
	v_add_u32_e32 v0, 0x4200, v16
	ds_write2_b32 v0, v209, v207 offset1:132
	v_add_u32_e32 v0, 0x4200, v17
	ds_write2_b32 v0, v210, v208 offset0:16 offset1:148
	v_add_u32_e32 v0, 0x4600, v16
	ds_write2_b32 v0, v205, v203 offset0:8 offset1:140
	v_add_u32_e32 v0, 0x4600, v17
	ds_write2_b32 v0, v206, v204 offset0:24 offset1:156
	v_add_u32_e32 v0, 0x6200, v16
	ds_write2_b32 v0, v12, v7 offset0:64 offset1:196
	v_add_u32_e32 v0, 0x6200, v17
	ds_write2_b32 v0, v13, v9 offset0:80 offset1:212
	v_add_u32_e32 v0, 0x6600, v16
	ds_write2_b32 v0, v4, v2 offset0:72 offset1:204
	v_add_u32_e32 v0, 0x6600, v17
	s_and_b64 vcc, exec, s[22:23]
	ds_write2_b32 v0, v5, v3 offset0:88 offset1:220
	s_waitcnt lgkmcnt(0)
	s_barrier
	s_cbranch_vccz .LBB0_365
	v_mov_b32_e32 v187, v113
	s_lshl_b32 s10, s12, 7
	s_sub_i32 s4, s33, 36
	s_add_i32 s10, s10, s78
	v_lshrrev_b32_e32 v1, 4, v187
	s_ashr_i32 s5, s4, 31
	v_xor_b32_e32 v162, v1, v187
	v_bitop3_b32 v1, v1, 2, v187 bitop3:0x48
	s_ashr_i32 s11, s10, 6
	s_lshl_b64 s[8:9], s[4:5], 13
	v_bfe_u32 v0, v187, 2, 7
	v_lshlrev_b32_e32 v162, 5, v162
	v_lshlrev_b32_e32 v1, 1, v1
	s_add_u32 s8, s90, s8
	v_bitop3_b32 v227, v1, 36, v162 bitop3:0xc8
	s_addc_u32 s9, s91, s9
	v_lshlrev_b32_e32 v162, 6, v0
	v_lshl_add_u32 v228, v0, 2, 0
	v_lshl_add_u64 v[0:1], s[8:9], 0, v[162:163]
	v_lshlrev_b32_e32 v162, 4, v187
	v_and_b32_e32 v162, 48, v162
	v_lshl_add_u64 v[0:1], v[0:1], 0, v[162:163]
	s_mov_b32 s13, 0
	s_mov_b64 s[8:9], -1

.LBB0_371:
	s_or_b64 exec, exec, s[4:5]
	s_and_b64 s[4:5], s[14:15], exec
	s_cselect_b32 s8, s81, s83
	s_cselect_b32 s9, s80, s82
	s_lshl_b64 s[4:5], s[72:73], 2
	s_add_u32 s4, s9, s4
	s_addc_u32 s5, s8, s5
	s_waitcnt lgkmcnt(0)
	s_barrier
	global_load_dword v0, v202, s[4:5]
	global_load_dword v1, v202, s[4:5] offset:64
	v_add_u32_e32 v162, s64, v18
	ds_read_b128 v[228:231], v162
	v_add_u32_e32 v187, s64, v19
	s_lshl_b32 s29, s12, 7
	v_and_b32_e32 v11, 28, v11
	s_add_i32 s29, s29, s78
	s_waitcnt lgkmcnt(0)
	v_add_f32_e32 v162, v228, v229
	v_add_f32_e32 v162, v230, v162
	v_add_f32_e32 v162, v231, v162
	v_fmamk_f32 v162, v162, 0x3c000000, v188
	v_rsq_f32_e32 v162, v162
	v_cmp_gt_u32_e64 s[10:11], 64, v8
	s_mov_b64 s[4:5], -1
	s_and_b64 vcc, exec, s[94:95]
	v_mul_f32_e32 v225, v225, v162
	v_mul_f32_e32 v162, v226, v162
	s_waitcnt vmcnt(1)
	v_mul_f32_e32 v225, v0, v225
	s_waitcnt vmcnt(0)
	v_mul_f32_e32 v162, v1, v162
	ds_write_b32 v16, v225
	ds_write_b32 v17, v162 offset:64
	ds_read_b128 v[226:229], v187
	v_add_u32_e32 v187, s64, v20
	s_waitcnt lgkmcnt(0)
	v_add_f32_e32 v162, v226, v227
	v_add_f32_e32 v162, v228, v162
	v_add_f32_e32 v162, v229, v162
	v_fmamk_f32 v162, v162, 0x3c000000, v188
	v_rsq_f32_e32 v162, v162
	s_nop 0
	v_mul_f32_e32 v223, v223, v162
	v_mul_f32_e32 v162, v224, v162
	v_mul_f32_e32 v223, v0, v223
	v_mul_f32_e32 v162, v1, v162
	ds_write_b32 v166, v223
	ds_write_b32 v167, v162 offset:64
	ds_read_b128 v[224:227], v187
	v_add_u32_e32 v187, s64, v21
	s_waitcnt lgkmcnt(0)
	v_add_f32_e32 v162, v224, v225
	v_add_f32_e32 v162, v226, v162
	v_add_f32_e32 v162, v227, v162
	v_fmamk_f32 v162, v162, 0x3c000000, v188
	v_rsq_f32_e32 v162, v162
	s_nop 0
	v_mul_f32_e32 v221, v221, v162
	v_mul_f32_e32 v162, v222, v162
	v_mul_f32_e32 v221, v0, v221
	v_mul_f32_e32 v162, v1, v162
	ds_write_b32 v168, v221
	ds_write_b32 v169, v162 offset:64
	ds_read_b128 v[222:225], v187
	v_add_u32_e32 v187, s64, v22
	s_waitcnt lgkmcnt(0)
	v_add_f32_e32 v162, v222, v223
	v_add_f32_e32 v162, v224, v162
	v_add_f32_e32 v162, v225, v162
	v_fmamk_f32 v162, v162, 0x3c000000, v188
	v_rsq_f32_e32 v162, v162
	s_nop 0
	v_mul_f32_e32 v219, v219, v162
	v_mul_f32_e32 v162, v220, v162
	v_mul_f32_e32 v219, v0, v219
	v_mul_f32_e32 v162, v1, v162
	ds_write_b32 v170, v219
	ds_write_b32 v171, v162 offset:64
	ds_read_b128 v[220:223], v187
	v_add_u32_e32 v187, s64, v23
	s_waitcnt lgkmcnt(0)
	v_add_f32_e32 v162, v220, v221
	v_add_f32_e32 v162, v222, v162
	v_add_f32_e32 v162, v223, v162
	v_fmamk_f32 v162, v162, 0x3c000000, v188
	v_rsq_f32_e32 v162, v162
	s_nop 0
	v_mul_f32_e32 v217, v217, v162
	v_mul_f32_e32 v162, v218, v162
	v_mul_f32_e32 v217, v0, v217
	v_mul_f32_e32 v162, v1, v162
	ds_write_b32 v172, v217
	ds_write_b32 v173, v162 offset:64
	ds_read_b128 v[218:221], v187
	v_add_u32_e32 v187, s64, v154
	s_waitcnt lgkmcnt(0)
	v_add_f32_e32 v162, v218, v219
	v_add_f32_e32 v162, v220, v162
	v_add_f32_e32 v162, v221, v162
	v_fmamk_f32 v162, v162, 0x3c000000, v188
	v_rsq_f32_e32 v162, v162
	s_nop 0
	v_mul_f32_e32 v215, v215, v162
	v_mul_f32_e32 v162, v216, v162
	v_mul_f32_e32 v215, v0, v215
	v_mul_f32_e32 v162, v1, v162
	ds_write_b32 v174, v215
	ds_write_b32 v175, v162 offset:64
	ds_read_b128 v[216:219], v187
	v_add_u32_e32 v187, s64, v155
	s_waitcnt lgkmcnt(0)
	v_add_f32_e32 v162, v216, v217
	v_add_f32_e32 v162, v218, v162
	v_add_f32_e32 v162, v219, v162
	v_fmamk_f32 v162, v162, 0x3c000000, v188
	v_rsq_f32_e32 v162, v162
	s_nop 0
	v_mul_f32_e32 v213, v213, v162
	v_mul_f32_e32 v162, v214, v162
	v_mul_f32_e32 v213, v0, v213
	v_mul_f32_e32 v162, v1, v162
	ds_write_b32 v176, v213
	ds_write_b32 v177, v162 offset:64
	ds_read_b128 v[214:217], v187
	v_add_u32_e32 v187, s64, v156
	s_waitcnt lgkmcnt(0)
	v_add_f32_e32 v162, v214, v215
	v_add_f32_e32 v162, v216, v162
	v_add_f32_e32 v162, v217, v162
	v_fmamk_f32 v162, v162, 0x3c000000, v188
	v_rsq_f32_e32 v162, v162
	s_nop 0
	v_mul_f32_e32 v211, v211, v162
	v_mul_f32_e32 v162, v212, v162
	v_mul_f32_e32 v211, v0, v211
	v_mul_f32_e32 v162, v1, v162
	ds_write_b32 v178, v211
	ds_write_b32 v179, v162 offset:64
	ds_read_b128 v[212:215], v187
	v_add_u32_e32 v187, s64, v157
	s_waitcnt lgkmcnt(0)
	v_add_f32_e32 v162, v212, v213
	v_add_f32_e32 v162, v214, v162
	v_add_f32_e32 v162, v215, v162
	v_fmamk_f32 v162, v162, 0x3c000000, v188
	v_rsq_f32_e32 v162, v162
	s_nop 0
	v_mul_f32_e32 v209, v209, v162
	v_mul_f32_e32 v162, v210, v162
	v_mul_f32_e32 v209, v0, v209
	v_mul_f32_e32 v162, v1, v162
	ds_write_b32 v180, v209
	ds_write_b32 v181, v162 offset:64
	ds_read_b128 v[210:213], v187
	v_add_u32_e32 v187, s64, v158
	s_waitcnt lgkmcnt(0)
	v_add_f32_e32 v162, v210, v211
	v_add_f32_e32 v162, v212, v162
	v_add_f32_e32 v162, v213, v162
	v_fmamk_f32 v162, v162, 0x3c000000, v188
	v_rsq_f32_e32 v162, v162
	s_nop 0
	v_mul_f32_e32 v207, v207, v162
	v_mul_f32_e32 v162, v208, v162
	v_mul_f32_e32 v207, v0, v207
	v_mul_f32_e32 v162, v1, v162
	ds_write_b32 v182, v207
	ds_write_b32 v183, v162 offset:64
	ds_read_b128 v[208:211], v187
	v_add_u32_e32 v187, s64, v159
	s_waitcnt lgkmcnt(0)
	v_add_f32_e32 v162, v208, v209
	v_add_f32_e32 v162, v210, v162
	v_add_f32_e32 v162, v211, v162
	v_fmamk_f32 v162, v162, 0x3c000000, v188
	v_rsq_f32_e32 v162, v162
	s_nop 0
	v_mul_f32_e32 v205, v205, v162
	v_mul_f32_e32 v162, v206, v162
	v_mul_f32_e32 v205, v0, v205
	v_mul_f32_e32 v162, v1, v162
	ds_write_b32 v184, v205
	ds_write_b32 v185, v162 offset:64
	ds_read_b128 v[206:209], v187
	v_add_u32_e32 v187, s64, v160
	s_waitcnt lgkmcnt(0)
	v_add_f32_e32 v162, v206, v207
	v_add_f32_e32 v162, v208, v162
	v_add_f32_e32 v162, v209, v162
	v_fmamk_f32 v162, v162, 0x3c000000, v188
	v_rsq_f32_e32 v162, v162
	s_nop 0
	v_mul_f32_e32 v203, v203, v162
	v_mul_f32_e32 v162, v204, v162
	v_mul_f32_e32 v203, v0, v203
	v_mul_f32_e32 v162, v1, v162
	ds_write_b32 v192, v203
	ds_write_b32 v193, v162 offset:64
	ds_read_b128 v[204:207], v187
	v_add_u32_e32 v187, s64, v161
	v_lshl_add_u32 v203, v11, 2, s24
	s_waitcnt lgkmcnt(0)
	v_add_f32_e32 v162, v204, v205
	v_add_f32_e32 v162, v206, v162
	v_add_f32_e32 v162, v207, v162
	v_fmamk_f32 v162, v162, 0x3c000000, v188
	v_rsq_f32_e32 v162, v162
	s_nop 0
	v_mul_f32_e32 v12, v12, v162
	v_mul_f32_e32 v13, v13, v162
	v_mul_f32_e32 v12, v0, v12
	v_mul_f32_e32 v13, v1, v13
	ds_write_b32 v194, v12
	ds_write_b32 v195, v13 offset:64
	ds_read_b128 v[204:207], v187
	v_add_u32_e32 v13, s64, v164
	v_add_u32_e32 v187, s64, v165
	v_lshlrev_b32_e32 v162, 2, v8
	s_waitcnt lgkmcnt(0)
	v_add_f32_e32 v12, v204, v205
	v_add_f32_e32 v12, v206, v12
	v_add_f32_e32 v12, v207, v12
	v_fmamk_f32 v12, v12, 0x3c000000, v188
	v_rsq_f32_e32 v12, v12
	v_add_u32_e32 v204, v10, v14
	v_and_b32_e32 v10, 8, v6
	v_cmp_eq_u32_e64 s[8:9], 0, v10
	v_mul_f32_e32 v7, v7, v12
	v_mul_f32_e32 v9, v9, v12
	v_mul_f32_e32 v7, v0, v7
	v_mul_f32_e32 v9, v1, v9
	ds_write_b32 v196, v7
	ds_write_b32 v197, v9 offset:64
	ds_read_b128 v[206:209], v13
	v_xor_b32_e32 v7, 32, v8
	v_add_u32_e32 v12, s29, v204
	s_waitcnt lgkmcnt(0)
	v_add_f32_e32 v9, v206, v207
	v_add_f32_e32 v9, v208, v9
	v_add_f32_e32 v9, v209, v9
	v_fmamk_f32 v9, v9, 0x3c000000, v188
	v_rsq_f32_e32 v9, v9
	v_lshl_add_u32 v206, v7, 2, 0
	v_mul_lo_u32 v207, v204, s38
	v_mul_f32_e32 v4, v4, v9
	v_mul_f32_e32 v5, v5, v9
	v_mul_f32_e32 v4, v0, v4
	v_mul_f32_e32 v5, v1, v5
	ds_write_b32 v198, v4
	ds_write_b32 v199, v5 offset:64
	ds_read_b128 v[4:7], v187
	v_lshlrev_b32_e32 v9, 2, v207
	v_add3_u32 v205, 0, v162, v9
	s_waitcnt lgkmcnt(0)
	v_add_f32_e32 v4, v4, v5
	v_add_f32_e32 v4, v6, v4
	v_add_f32_e32 v4, v7, v4
	v_fmamk_f32 v4, v4, 0x3c000000, v188
	v_rsq_f32_e32 v4, v4
	s_nop 0
	v_mul_f32_e32 v2, v2, v4
	v_mul_f32_e32 v3, v3, v4
	v_mul_f32_e32 v0, v0, v2
	v_mul_f32_e32 v1, v1, v3
	ds_write_b32 v200, v0
	ds_write_b32 v201, v1 offset:64
	s_waitcnt lgkmcnt(0)
	s_barrier
	ds_read_b128 v[0:3], v205
	s_cbranch_vccz .LBB0_373
	v_lshrrev_b32_e32 v4, 6, v12
	v_cndmask_b32_e64 v4, v204, v4, s[10:11]
	v_lshlrev_b32_e32 v4, 7, v4
	v_and_b32_e32 v4, 0x1f80, v4
	v_add_u32_e32 v9, v203, v4
	ds_read_b128 v[4:7], v9 offset:8192
	v_lshl_add_u32 v10, v207, 2, v206
	ds_read_b128 v[208:211], v10
	ds_read_b128 v[212:215], v9
	s_mov_b64 s[4:5], 0
	s_waitcnt lgkmcnt(2)
	v_xor_b32_e32 v9, 0x80000000, v6
	v_xor_b32_e32 v10, 0x80000000, v7
	v_xor_b32_e32 v11, 0x80000000, v4
	v_xor_b32_e32 v13, 0x80000000, v5
	v_cndmask_b32_e64 v5, v5, v13, s[8:9]
	v_cndmask_b32_e64 v4, v4, v11, s[8:9]
	v_cndmask_b32_e64 v7, v7, v10, s[8:9]
	v_cndmask_b32_e64 v6, v6, v9, s[8:9]
	s_waitcnt lgkmcnt(1)
	v_pk_mul_f32 v[6:7], v[210:211], v[6:7]
	v_pk_mul_f32 v[4:5], v[208:209], v[4:5]
	s_waitcnt lgkmcnt(0)
	v_pk_fma_f32 v[6:7], v[2:3], v[214:215], v[6:7]
	v_pk_fma_f32 v[4:5], v[0:1], v[212:213], v[4:5]
